# GEMM K-loops: uniform vmcnt(10) ahead of every phase's first barrier instead of vmcnt(6) at phases 4/8 (staged half-tiles get 5 phases to land)
# baseline (speedup 1.0000x reference)
.LBB0_262:
	ds_read_b128 v[128:131], v181
	ds_read_b128 v[132:135], v181 offset:1024
	ds_read_b128 v[136:139], v181 offset:2048
	ds_read_b128 v[140:143], v181 offset:3072
	s_add_u32 s6, s4, 0xfff80080
	s_addc_u32 s7, s5, -1
	s_cmp_eq_u32 s37, 28
	s_cselect_b32 s9, s10, s7
	s_cselect_b32 s8, s11, s6
	s_cselect_b32 s7, s20, s36
	s_cselect_b32 s6, s34, s35
	v_lshl_add_u64 v[176:177], s[4:5], 0, v[158:159]
	s_add_i32 m0, s44, 0xc000
	ds_read_b128 v[144:147], v182
	ds_read_b128 v[168:171], v182 offset:1024
	ds_read_b128 v[172:175], v182 offset:2048
	ds_read_b128 v[184:187], v182 offset:3072
	ds_read_b128 v[188:191], v182 offset:4096
	ds_read_b128 v[192:195], v182 offset:5120
	ds_read_b128 v[196:199], v182 offset:6144
	ds_read_b128 v[200:203], v182 offset:7168
	global_load_lds_dwordx4 v[176:177], off
	v_lshl_add_u64 v[176:177], s[4:5], 0, v[160:161]
	s_add_i32 m0, s44, 0xe000
	s_nop 0
	global_load_lds_dwordx4 v[176:177], off
	s_waitcnt lgkmcnt(8)
	s_waitcnt vmcnt(10)
	s_barrier
	s_waitcnt lgkmcnt(0)
	s_setprio 1
	s_waitcnt lgkmcnt(0)
	v_mfma_f32_16x16x32_bf16 v[124:127], v[128:131], v[144:147], v[124:127]
	v_mfma_f32_16x16x32_bf16 v[120:123], v[136:139], v[144:147], v[120:123]
	v_mfma_f32_16x16x32_bf16 v[108:111], v[128:131], v[172:175], v[108:111]
	v_mfma_f32_16x16x32_bf16 v[104:107], v[136:139], v[172:175], v[104:107]
	v_mfma_f32_16x16x32_bf16 v[92:95], v[128:131], v[188:191], v[92:95]
	v_mfma_f32_16x16x32_bf16 v[88:91], v[136:139], v[188:191], v[88:91]
	v_mfma_f32_16x16x32_bf16 v[76:79], v[128:131], v[196:199], v[76:79]
	v_mfma_f32_16x16x32_bf16 v[72:75], v[136:139], v[196:199], v[72:75]
	v_mfma_f32_16x16x32_bf16 v[124:127], v[132:135], v[168:171], v[124:127]
	v_mfma_f32_16x16x32_bf16 v[120:123], v[140:143], v[168:171], v[120:123]
	v_mfma_f32_16x16x32_bf16 v[108:111], v[132:135], v[184:187], v[108:111]
	v_mfma_f32_16x16x32_bf16 v[104:107], v[140:143], v[184:187], v[104:107]
	v_mfma_f32_16x16x32_bf16 v[92:95], v[132:135], v[192:195], v[92:95]
	v_mfma_f32_16x16x32_bf16 v[88:91], v[140:143], v[192:195], v[88:91]
	v_mfma_f32_16x16x32_bf16 v[76:79], v[132:135], v[200:203], v[76:79]
	v_mfma_f32_16x16x32_bf16 v[72:75], v[140:143], v[200:203], v[72:75]
	s_setprio 0
	s_barrier
	s_add_i32 s39, s80, s33
	v_lshl_add_u64 v[176:177], s[6:7], 0, v[150:151]
	s_mov_b32 m0, s39
	ds_read_b128 v[204:207], v183
	ds_read_b128 v[210:213], v183 offset:1024
	ds_read_b128 v[214:217], v183 offset:2048
	ds_read_b128 v[218:221], v183 offset:3072
	global_load_lds_dwordx4 v[176:177], off
	v_lshl_add_u64 v[222:223], s[6:7], 0, v[154:155]
	s_add_i32 m0, s39, 0x2000
	s_nop 0
	global_load_lds_dwordx4 v[222:223], off
	s_waitcnt vmcnt(10)
	s_barrier
	s_waitcnt lgkmcnt(0)
	s_setprio 1
	s_waitcnt lgkmcnt(0)
	v_mfma_f32_16x16x32_bf16 v[116:119], v[204:207], v[144:147], v[116:119]
	v_mfma_f32_16x16x32_bf16 v[112:115], v[214:217], v[144:147], v[112:115]
	v_mfma_f32_16x16x32_bf16 v[100:103], v[204:207], v[172:175], v[100:103]
	v_mfma_f32_16x16x32_bf16 v[96:99], v[214:217], v[172:175], v[96:99]
	v_mfma_f32_16x16x32_bf16 v[84:87], v[204:207], v[188:191], v[84:87]
	v_mfma_f32_16x16x32_bf16 v[80:83], v[214:217], v[188:191], v[80:83]
	v_mfma_f32_16x16x32_bf16 v[68:71], v[204:207], v[196:199], v[68:71]
	v_mfma_f32_16x16x32_bf16 v[64:67], v[214:217], v[196:199], v[64:67]
	v_mfma_f32_16x16x32_bf16 v[116:119], v[210:213], v[168:171], v[116:119]
	v_mfma_f32_16x16x32_bf16 v[112:115], v[218:221], v[168:171], v[112:115]
	v_mfma_f32_16x16x32_bf16 v[100:103], v[210:213], v[184:187], v[100:103]
	v_mfma_f32_16x16x32_bf16 v[96:99], v[218:221], v[184:187], v[96:99]
	v_mfma_f32_16x16x32_bf16 v[84:87], v[210:213], v[192:195], v[84:87]
	v_mfma_f32_16x16x32_bf16 v[80:83], v[218:221], v[192:195], v[80:83]
	v_mfma_f32_16x16x32_bf16 v[68:71], v[210:213], v[200:203], v[68:71]
	v_mfma_f32_16x16x32_bf16 v[64:67], v[218:221], v[200:203], v[64:67]
	s_setprio 0
	s_mov_b32 m0, s44
	v_lshl_add_u64 v[224:225], s[8:9], 0, v[148:149]
	s_barrier
	ds_read_b128 v[144:147], v182 offset:16384
	ds_read_b128 v[168:171], v182 offset:17408
	ds_read_b128 v[172:175], v182 offset:18432
	ds_read_b128 v[184:187], v182 offset:19456
	ds_read_b128 v[188:191], v182 offset:20480
	ds_read_b128 v[192:195], v182 offset:21504
	ds_read_b128 v[196:199], v182 offset:22528
	ds_read_b128 v[200:203], v182 offset:23552
	global_load_lds_dwordx4 v[224:225], off
	v_lshl_add_u64 v[226:227], s[8:9], 0, v[152:153]
	s_mov_b32 m0, s45
	s_nop 0
	global_load_lds_dwordx4 v[226:227], off
	s_waitcnt vmcnt(10)
	s_barrier
	s_waitcnt lgkmcnt(0)
	s_setprio 1
	s_waitcnt lgkmcnt(0)
	v_mfma_f32_16x16x32_bf16 v[60:63], v[128:131], v[144:147], v[60:63]
	v_mfma_f32_16x16x32_bf16 v[56:59], v[136:139], v[144:147], v[56:59]
	v_mfma_f32_16x16x32_bf16 v[44:47], v[128:131], v[172:175], v[44:47]
	v_mfma_f32_16x16x32_bf16 v[40:43], v[136:139], v[172:175], v[40:43]
	v_mfma_f32_16x16x32_bf16 v[28:31], v[128:131], v[188:191], v[28:31]
	v_mfma_f32_16x16x32_bf16 v[24:27], v[136:139], v[188:191], v[24:27]
	v_mfma_f32_16x16x32_bf16 v[12:15], v[128:131], v[196:199], v[12:15]
	v_mfma_f32_16x16x32_bf16 v[8:11], v[136:139], v[196:199], v[8:11]
	v_mfma_f32_16x16x32_bf16 v[60:63], v[132:135], v[168:171], v[60:63]
	v_mfma_f32_16x16x32_bf16 v[56:59], v[140:143], v[168:171], v[56:59]
	v_mfma_f32_16x16x32_bf16 v[44:47], v[132:135], v[184:187], v[44:47]
	v_mfma_f32_16x16x32_bf16 v[40:43], v[140:143], v[184:187], v[40:43]
	v_mfma_f32_16x16x32_bf16 v[28:31], v[132:135], v[192:195], v[28:31]
	v_mfma_f32_16x16x32_bf16 v[24:27], v[140:143], v[192:195], v[24:27]
	v_mfma_f32_16x16x32_bf16 v[12:15], v[132:135], v[200:203], v[12:15]
	v_mfma_f32_16x16x32_bf16 v[8:11], v[140:143], v[200:203], v[8:11]
	s_setprio 0
	s_barrier
	s_add_u32 s78, s6, 0x80000
	s_addc_u32 s79, s7, 0
	s_add_i32 s39, s81, s33
	v_lshl_add_u64 v[128:129], s[78:79], 0, v[150:151]
	s_mov_b32 m0, s39
	s_nop 0
	global_load_lds_dwordx4 v[128:129], off
	v_lshl_add_u64 v[128:129], s[78:79], 0, v[154:155]
	s_add_i32 m0, s39, 0x2000
	s_nop 0
	global_load_lds_dwordx4 v[128:129], off
	s_waitcnt vmcnt(10)
	s_barrier
	s_setprio 1
	v_mfma_f32_16x16x32_bf16 v[52:55], v[204:207], v[144:147], v[52:55]
	v_mfma_f32_16x16x32_bf16 v[48:51], v[214:217], v[144:147], v[48:51]
	v_mfma_f32_16x16x32_bf16 v[36:39], v[204:207], v[172:175], v[36:39]
	v_mfma_f32_16x16x32_bf16 v[32:35], v[214:217], v[172:175], v[32:35]
	v_mfma_f32_16x16x32_bf16 v[20:23], v[204:207], v[188:191], v[20:23]
	v_mfma_f32_16x16x32_bf16 v[16:19], v[214:217], v[188:191], v[16:19]
	v_mfma_f32_16x16x32_bf16 v[4:7], v[204:207], v[196:199], v[4:7]
	v_mfma_f32_16x16x32_bf16 v[0:3], v[214:217], v[196:199], v[0:3]
	v_mfma_f32_16x16x32_bf16 v[52:55], v[210:213], v[168:171], v[52:55]
	v_mfma_f32_16x16x32_bf16 v[48:51], v[218:221], v[168:171], v[48:51]
	v_mfma_f32_16x16x32_bf16 v[36:39], v[210:213], v[184:187], v[36:39]
	v_mfma_f32_16x16x32_bf16 v[32:35], v[218:221], v[184:187], v[32:35]
	v_mfma_f32_16x16x32_bf16 v[20:23], v[210:213], v[192:195], v[20:23]
	v_mfma_f32_16x16x32_bf16 v[16:19], v[218:221], v[192:195], v[16:19]
	v_mfma_f32_16x16x32_bf16 v[4:7], v[210:213], v[200:203], v[4:7]
	v_mfma_f32_16x16x32_bf16 v[0:3], v[218:221], v[200:203], v[0:3]
	s_setprio 0
	s_add_i32 s39, 0, 0x18000
	v_add_u32_e32 v140, s39, v180
	s_barrier
	ds_read_b128 v[128:131], v140
	ds_read_b128 v[132:135], v140 offset:1024
	ds_read_b128 v[136:139], v140 offset:2048
	ds_read_b128 v[140:143], v140 offset:3072
	s_add_u32 s8, s8, 0x80000
	s_addc_u32 s9, s9, 0
	s_mov_b32 m0, s51
	v_lshl_add_u64 v[204:205], s[8:9], 0, v[148:149]
	ds_read_b128 v[144:147], v182 offset:32768
	ds_read_b128 v[168:171], v182 offset:33792
	ds_read_b128 v[172:175], v182 offset:34816
	ds_read_b128 v[184:187], v182 offset:35840
	ds_read_b128 v[188:191], v182 offset:36864
	ds_read_b128 v[192:195], v182 offset:37888
	ds_read_b128 v[196:199], v182 offset:38912
	ds_read_b128 v[200:203], v182 offset:39936
	global_load_lds_dwordx4 v[204:205], off
	v_lshl_add_u64 v[204:205], s[8:9], 0, v[152:153]
	s_mov_b32 m0, s55
	s_nop 0
	global_load_lds_dwordx4 v[204:205], off
	s_waitcnt lgkmcnt(8)
	s_waitcnt vmcnt(10)
	s_barrier
	s_waitcnt lgkmcnt(0)
	s_setprio 1
	s_waitcnt lgkmcnt(0)
	v_mfma_f32_16x16x32_bf16 v[124:127], v[128:131], v[144:147], v[124:127]
	v_mfma_f32_16x16x32_bf16 v[120:123], v[136:139], v[144:147], v[120:123]
	v_mfma_f32_16x16x32_bf16 v[108:111], v[128:131], v[172:175], v[108:111]
	v_mfma_f32_16x16x32_bf16 v[104:107], v[136:139], v[172:175], v[104:107]
	v_mfma_f32_16x16x32_bf16 v[92:95], v[128:131], v[188:191], v[92:95]
	v_mfma_f32_16x16x32_bf16 v[88:91], v[136:139], v[188:191], v[88:91]
	v_mfma_f32_16x16x32_bf16 v[76:79], v[128:131], v[196:199], v[76:79]
	v_mfma_f32_16x16x32_bf16 v[72:75], v[136:139], v[196:199], v[72:75]
	v_mfma_f32_16x16x32_bf16 v[124:127], v[132:135], v[168:171], v[124:127]
	v_mfma_f32_16x16x32_bf16 v[120:123], v[140:143], v[168:171], v[120:123]
	v_mfma_f32_16x16x32_bf16 v[108:111], v[132:135], v[184:187], v[108:111]
	v_mfma_f32_16x16x32_bf16 v[104:107], v[140:143], v[184:187], v[104:107]
	v_mfma_f32_16x16x32_bf16 v[92:95], v[132:135], v[192:195], v[92:95]
	v_mfma_f32_16x16x32_bf16 v[88:91], v[140:143], v[192:195], v[88:91]
	v_mfma_f32_16x16x32_bf16 v[76:79], v[132:135], v[200:203], v[76:79]
	v_mfma_f32_16x16x32_bf16 v[72:75], v[140:143], v[200:203], v[72:75]
	s_setprio 0
	s_barrier
	s_add_i32 s8, 0, 0x1c000
	s_add_i32 s9, s39, s33
	v_add_u32_e32 v156, s8, v180
	v_lshl_add_u64 v[176:177], v[176:177], 0, s[24:25]
	s_mov_b32 m0, s9
	ds_read_b128 v[204:207], v156
	ds_read_b128 v[210:213], v156 offset:1024
	ds_read_b128 v[214:217], v156 offset:2048
	ds_read_b128 v[218:221], v156 offset:3072
	global_load_lds_dwordx4 v[176:177], off
	v_lshl_add_u64 v[176:177], v[222:223], 0, s[24:25]
	s_add_i32 m0, s9, 0x2000
	s_nop 0
	global_load_lds_dwordx4 v[176:177], off
	s_waitcnt vmcnt(10)
	s_barrier
	s_waitcnt lgkmcnt(0)
	s_setprio 1
	s_waitcnt lgkmcnt(0)
	v_mfma_f32_16x16x32_bf16 v[116:119], v[204:207], v[144:147], v[116:119]
	v_mfma_f32_16x16x32_bf16 v[112:115], v[214:217], v[144:147], v[112:115]
	v_mfma_f32_16x16x32_bf16 v[100:103], v[204:207], v[172:175], v[100:103]
	v_mfma_f32_16x16x32_bf16 v[96:99], v[214:217], v[172:175], v[96:99]
	v_mfma_f32_16x16x32_bf16 v[84:87], v[204:207], v[188:191], v[84:87]
	v_mfma_f32_16x16x32_bf16 v[80:83], v[214:217], v[188:191], v[80:83]
	v_mfma_f32_16x16x32_bf16 v[68:71], v[204:207], v[196:199], v[68:71]
	v_mfma_f32_16x16x32_bf16 v[64:67], v[214:217], v[196:199], v[64:67]
	v_mfma_f32_16x16x32_bf16 v[116:119], v[210:213], v[168:171], v[116:119]
	v_mfma_f32_16x16x32_bf16 v[112:115], v[218:221], v[168:171], v[112:115]
	v_mfma_f32_16x16x32_bf16 v[100:103], v[210:213], v[184:187], v[100:103]
	v_mfma_f32_16x16x32_bf16 v[96:99], v[218:221], v[184:187], v[96:99]
	v_mfma_f32_16x16x32_bf16 v[84:87], v[210:213], v[192:195], v[84:87]
	v_mfma_f32_16x16x32_bf16 v[80:83], v[218:221], v[192:195], v[80:83]
	v_mfma_f32_16x16x32_bf16 v[68:71], v[210:213], v[200:203], v[68:71]
	v_mfma_f32_16x16x32_bf16 v[64:67], v[218:221], v[200:203], v[64:67]
	s_setprio 0
	s_mov_b32 m0, s83
	v_lshl_add_u64 v[176:177], v[224:225], 0, s[24:25]
	s_barrier
	ds_read_b128 v[144:147], v182 offset:49152
	ds_read_b128 v[168:171], v182 offset:50176
	ds_read_b128 v[172:175], v182 offset:51200
	ds_read_b128 v[184:187], v182 offset:52224
	ds_read_b128 v[188:191], v182 offset:53248
	ds_read_b128 v[192:195], v182 offset:54272
	ds_read_b128 v[196:199], v182 offset:55296
	ds_read_b128 v[200:203], v182 offset:56320
	global_load_lds_dwordx4 v[176:177], off
	v_lshl_add_u64 v[176:177], v[226:227], 0, s[24:25]
	s_mov_b32 m0, s91
	s_nop 0
	global_load_lds_dwordx4 v[176:177], off
	s_waitcnt vmcnt(10)
	s_barrier
	s_waitcnt lgkmcnt(0)
	s_setprio 1
	s_waitcnt lgkmcnt(0)
	v_mfma_f32_16x16x32_bf16 v[60:63], v[128:131], v[144:147], v[60:63]
	v_mfma_f32_16x16x32_bf16 v[56:59], v[136:139], v[144:147], v[56:59]
	v_mfma_f32_16x16x32_bf16 v[44:47], v[128:131], v[172:175], v[44:47]
	v_mfma_f32_16x16x32_bf16 v[40:43], v[136:139], v[172:175], v[40:43]
	v_mfma_f32_16x16x32_bf16 v[28:31], v[128:131], v[188:191], v[28:31]
	v_mfma_f32_16x16x32_bf16 v[24:27], v[136:139], v[188:191], v[24:27]
	v_mfma_f32_16x16x32_bf16 v[12:15], v[128:131], v[196:199], v[12:15]
	v_mfma_f32_16x16x32_bf16 v[8:11], v[136:139], v[196:199], v[8:11]
	v_mfma_f32_16x16x32_bf16 v[60:63], v[132:135], v[168:171], v[60:63]
	v_mfma_f32_16x16x32_bf16 v[56:59], v[140:143], v[168:171], v[56:59]
	v_mfma_f32_16x16x32_bf16 v[44:47], v[132:135], v[184:187], v[44:47]
	v_mfma_f32_16x16x32_bf16 v[40:43], v[140:143], v[184:187], v[40:43]
	v_mfma_f32_16x16x32_bf16 v[28:31], v[132:135], v[192:195], v[28:31]
	v_mfma_f32_16x16x32_bf16 v[24:27], v[140:143], v[192:195], v[24:27]
	v_mfma_f32_16x16x32_bf16 v[12:15], v[132:135], v[200:203], v[12:15]
	v_mfma_f32_16x16x32_bf16 v[8:11], v[140:143], v[200:203], v[8:11]
	s_setprio 0
	s_barrier
	s_add_u32 s6, s6, 0x80080
	s_addc_u32 s7, s7, 0
	s_add_i32 s8, s8, s33
	v_lshl_add_u64 v[128:129], s[6:7], 0, v[150:151]
	s_mov_b32 m0, s8
	s_nop 0
	global_load_lds_dwordx4 v[128:129], off
	v_lshl_add_u64 v[128:129], s[6:7], 0, v[154:155]
	s_add_i32 m0, s8, 0x2000
	s_nop 0
	global_load_lds_dwordx4 v[128:129], off
	s_waitcnt vmcnt(10)
	s_barrier
	s_setprio 1
	v_mfma_f32_16x16x32_bf16 v[52:55], v[204:207], v[144:147], v[52:55]
	v_mfma_f32_16x16x32_bf16 v[48:51], v[214:217], v[144:147], v[48:51]
	v_mfma_f32_16x16x32_bf16 v[36:39], v[204:207], v[172:175], v[36:39]
	v_mfma_f32_16x16x32_bf16 v[32:35], v[214:217], v[172:175], v[32:35]
	v_mfma_f32_16x16x32_bf16 v[20:23], v[204:207], v[188:191], v[20:23]
	v_mfma_f32_16x16x32_bf16 v[16:19], v[214:217], v[188:191], v[16:19]
	v_mfma_f32_16x16x32_bf16 v[4:7], v[204:207], v[196:199], v[4:7]
	v_mfma_f32_16x16x32_bf16 v[0:3], v[214:217], v[196:199], v[0:3]
	v_mfma_f32_16x16x32_bf16 v[52:55], v[210:213], v[168:171], v[52:55]
	v_mfma_f32_16x16x32_bf16 v[48:51], v[218:221], v[168:171], v[48:51]
	v_mfma_f32_16x16x32_bf16 v[36:39], v[210:213], v[184:187], v[36:39]
	v_mfma_f32_16x16x32_bf16 v[32:35], v[218:221], v[184:187], v[32:35]
	v_mfma_f32_16x16x32_bf16 v[20:23], v[210:213], v[192:195], v[20:23]
	v_mfma_f32_16x16x32_bf16 v[16:19], v[218:221], v[192:195], v[16:19]
	v_mfma_f32_16x16x32_bf16 v[4:7], v[210:213], v[200:203], v[4:7]
	v_mfma_f32_16x16x32_bf16 v[0:3], v[218:221], v[200:203], v[0:3]
	s_setprio 0
	s_add_i32 s37, s37, 2
	s_add_u32 s4, s4, 0x100
	s_addc_u32 s5, s5, 0
	s_add_u32 s35, s35, 0x100
	s_addc_u32 s36, s36, 0
	s_cmp_gt_u32 s37, 29
	s_barrier
	s_cbranch_scc0 .LBB0_262
	v_mov_b32_e32 v185, v179
	v_mov_b32_e32 v184, v178
	s_cmp_lt_i32 s90, 33
	s_mov_b64 s[4:5], -1
	s_cbranch_scc0 .LBB0_589
	s_cmp_gt_i32 s82, 3
	s_cbranch_scc0 .LBB0_586
	s_cmp_gt_u32 s82, 7
	s_cbranch_scc0 .LBB0_551
	s_cmp_gt_u32 s82, 15
	s_cbranch_scc0 .LBB0_548
	s_cmp_gt_u32 s82, 23
	s_cbranch_scc0 .LBB0_545
	s_cmp_gt_u32 s82, 27
	s_cbranch_scc0 .LBB0_486
	s_cmp_gt_u32 s82, 31
	s_cbranch_scc0 .LBB0_315
	s_cmp_gt_u32 s82, 35
	s_cbranch_scc0 .LBB0_280
	s_cmp_gt_u32 s82, 39
	s_cbranch_scc0 .LBB0_277
	s_lshl_b32 s4, s90, 8
	s_add_i32 s4, s4, s57
	v_lshl_add_u32 v128, v185, 3, s59
	v_add_u32_e32 v132, s4, v184
	v_ashrrev_i32_e32 v129, 31, v128
	v_mad_i64_i32 v[130:131], s[4:5], v132, s28, 0
	s_cmp_gt_u32 s82, 41
	s_mov_b64 s[4:5], -1
	v_lshl_add_u64 v[130:131], s[0:1], 0, v[130:131]
	v_lshlrev_b64 v[128:129], 1, v[128:129]
	v_add_u32_e32 v138, 16, v132
	v_add_u32_e32 v137, 32, v132
	v_add_u32_e32 v136, 48, v132
	v_add_u32_e32 v135, 0x80, v132
	v_add_u32_e32 v134, 0x90, v132
	v_add_u32_e32 v133, 0xa0, v132
	v_add_u32_e32 v132, 0xb0, v132
	s_cbranch_scc0 .LBB0_274
	s_lshl_b32 s20, s82, 8
	s_lshl_b64 s[4:5], s[20:21], 1
	v_lshl_add_u64 v[144:145], v[130:131], 0, s[4:5]
	v_cvt_pk_bf16_f32 v140, v124, v125
	v_cvt_pk_bf16_f32 v141, v126, v127
	v_cvt_pk_bf16_f32 v142, v120, v121
	v_cvt_pk_bf16_f32 v143, v122, v123
	v_lshl_add_u64 v[144:145], v[144:145], 0, v[128:129]
	global_store_dwordx4 v[144:145], v[140:143], off
	s_nop 1
	v_cvt_pk_bf16_f32 v140, v116, v117
	v_cvt_pk_bf16_f32 v141, v118, v119
	v_cvt_pk_bf16_f32 v142, v112, v113
	v_cvt_pk_bf16_f32 v143, v114, v115
	global_store_dwordx4 v[144:145], v[140:143], off offset:256
	v_mov_b64_e32 v[144:145], s[0:1]
	v_mad_i64_i32 v[146:147], s[6:7], v138, s28, v[144:145]
	v_lshl_add_u64 v[146:147], v[146:147], 0, s[4:5]
	v_cvt_pk_bf16_f32 v140, v108, v109
	v_cvt_pk_bf16_f32 v141, v110, v111
	v_cvt_pk_bf16_f32 v142, v104, v105
	v_cvt_pk_bf16_f32 v143, v106, v107
	v_lshl_add_u64 v[146:147], v[146:147], 0, v[128:129]
	global_store_dwordx4 v[146:147], v[140:143], off
	s_nop 1
	v_cvt_pk_bf16_f32 v140, v100, v101
	v_cvt_pk_bf16_f32 v141, v102, v103
	v_cvt_pk_bf16_f32 v142, v96, v97
	v_cvt_pk_bf16_f32 v143, v98, v99
	global_store_dwordx4 v[146:147], v[140:143], off offset:256
	v_mad_i64_i32 v[146:147], s[6:7], v137, s28, v[144:145]
	v_lshl_add_u64 v[146:147], v[146:147], 0, s[4:5]
	v_cvt_pk_bf16_f32 v140, v92, v93
	v_cvt_pk_bf16_f32 v141, v94, v95
	v_cvt_pk_bf16_f32 v142, v88, v89
	v_cvt_pk_bf16_f32 v143, v90, v91
	v_lshl_add_u64 v[146:147], v[146:147], 0, v[128:129]
	global_store_dwordx4 v[146:147], v[140:143], off
	s_nop 1
	v_cvt_pk_bf16_f32 v140, v84, v85
	v_cvt_pk_bf16_f32 v141, v86, v87
	v_cvt_pk_bf16_f32 v142, v80, v81
	v_cvt_pk_bf16_f32 v143, v82, v83
	global_store_dwordx4 v[146:147], v[140:143], off offset:256
	v_mad_i64_i32 v[146:147], s[6:7], v136, s28, v[144:145]
	v_lshl_add_u64 v[146:147], v[146:147], 0, s[4:5]
	v_cvt_pk_bf16_f32 v140, v76, v77
	v_cvt_pk_bf16_f32 v141, v78, v79
	v_cvt_pk_bf16_f32 v142, v72, v73
	v_cvt_pk_bf16_f32 v143, v74, v75
	v_lshl_add_u64 v[146:147], v[146:147], 0, v[128:129]
	global_store_dwordx4 v[146:147], v[140:143], off
	s_nop 1
	v_cvt_pk_bf16_f32 v140, v68, v69
	v_cvt_pk_bf16_f32 v141, v70, v71
	v_cvt_pk_bf16_f32 v142, v64, v65
	v_cvt_pk_bf16_f32 v143, v66, v67
	global_store_dwordx4 v[146:147], v[140:143], off offset:256
	v_mad_i64_i32 v[146:147], s[6:7], v135, s28, v[144:145]
	v_lshl_add_u64 v[146:147], v[146:147], 0, s[4:5]
	v_cvt_pk_bf16_f32 v140, v60, v61
	v_cvt_pk_bf16_f32 v141, v62, v63
	v_cvt_pk_bf16_f32 v142, v56, v57
	v_cvt_pk_bf16_f32 v143, v58, v59
	v_lshl_add_u64 v[146:147], v[146:147], 0, v[128:129]
	global_store_dwordx4 v[146:147], v[140:143], off
	s_nop 1
	v_cvt_pk_bf16_f32 v140, v52, v53
	v_cvt_pk_bf16_f32 v141, v54, v55
	v_cvt_pk_bf16_f32 v142, v48, v49
	v_cvt_pk_bf16_f32 v143, v50, v51
	global_store_dwordx4 v[146:147], v[140:143], off offset:256
	v_mad_i64_i32 v[146:147], s[6:7], v134, s28, v[144:145]
	v_lshl_add_u64 v[146:147], v[146:147], 0, s[4:5]
	v_cvt_pk_bf16_f32 v140, v44, v45
	v_cvt_pk_bf16_f32 v141, v46, v47
	v_cvt_pk_bf16_f32 v142, v40, v41
	v_cvt_pk_bf16_f32 v143, v42, v43
	v_lshl_add_u64 v[146:147], v[146:147], 0, v[128:129]
	global_store_dwordx4 v[146:147], v[140:143], off
	s_nop 1
	v_cvt_pk_bf16_f32 v140, v36, v37
	v_cvt_pk_bf16_f32 v141, v38, v39
	v_cvt_pk_bf16_f32 v142, v32, v33
	v_cvt_pk_bf16_f32 v143, v34, v35
	global_store_dwordx4 v[146:147], v[140:143], off offset:256
	v_mad_i64_i32 v[146:147], s[6:7], v133, s28, v[144:145]
	v_lshl_add_u64 v[146:147], v[146:147], 0, s[4:5]
	v_cvt_pk_bf16_f32 v140, v28, v29
	v_cvt_pk_bf16_f32 v141, v30, v31
	v_cvt_pk_bf16_f32 v142, v24, v25
	v_cvt_pk_bf16_f32 v143, v26, v27
	v_lshl_add_u64 v[146:147], v[146:147], 0, v[128:129]
	v_mad_i64_i32 v[144:145], s[6:7], v132, s28, v[144:145]
	global_store_dwordx4 v[146:147], v[140:143], off
	v_lshl_add_u64 v[144:145], v[144:145], 0, s[4:5]
	v_lshl_add_u64 v[144:145], v[144:145], 0, v[128:129]
	v_cvt_pk_bf16_f32 v140, v20, v21
	v_cvt_pk_bf16_f32 v141, v22, v23
	v_cvt_pk_bf16_f32 v142, v16, v17
	v_cvt_pk_bf16_f32 v143, v18, v19
	global_store_dwordx4 v[146:147], v[140:143], off offset:256
	s_mov_b64 s[4:5], 0
	s_nop 0
	v_cvt_pk_bf16_f32 v140, v12, v13
	v_cvt_pk_bf16_f32 v141, v14, v15
	v_cvt_pk_bf16_f32 v142, v8, v9
	v_cvt_pk_bf16_f32 v143, v10, v11
	global_store_dwordx4 v[144:145], v[140:143], off
	s_nop 1
	v_cvt_pk_bf16_f32 v140, v4, v5
	v_cvt_pk_bf16_f32 v141, v6, v7
	v_cvt_pk_bf16_f32 v142, v0, v1
	v_cvt_pk_bf16_f32 v143, v2, v3
	global_store_dwordx4 v[144:145], v[140:143], off offset:256

.LBB0_974:
	ds_read_b128 v[150:153], v147
	ds_read_b128 v[154:157], v147 offset:1024
	ds_read_b128 v[158:161], v147 offset:2048
	ds_read_b128 v[162:165], v147 offset:3072
	s_add_u32 s16, s14, 0x100
	s_addc_u32 s17, s15, 0
	s_cmp_eq_u32 s44, 52
	s_cselect_b32 s21, s3, s17
	s_cselect_b32 s20, s2, s16
	s_cselect_b32 s19, s5, s43
	s_cselect_b32 s18, s4, s42
	v_lshl_add_u64 v[198:199], s[14:15], 0, v[136:137]
	s_add_i32 m0, s24, 0xc000
	ds_read_b128 v[166:169], v148
	ds_read_b128 v[170:173], v148 offset:1024
	ds_read_b128 v[174:177], v148 offset:2048
	ds_read_b128 v[178:181], v148 offset:3072
	ds_read_b128 v[182:185], v148 offset:4096
	ds_read_b128 v[186:189], v148 offset:5120
	ds_read_b128 v[190:193], v148 offset:6144
	ds_read_b128 v[194:197], v148 offset:7168
	global_load_lds_dwordx4 v[198:199], off
	v_lshl_add_u64 v[198:199], s[14:15], 0, v[138:139]
	s_add_i32 m0, s24, 0xe000
	s_nop 0
	global_load_lds_dwordx4 v[198:199], off
	s_waitcnt lgkmcnt(8)
	s_waitcnt vmcnt(10)
	s_barrier
	s_waitcnt lgkmcnt(0)
	s_setprio 1
	s_waitcnt lgkmcnt(0)
	v_mfma_f32_16x16x32_bf16 v[124:127], v[150:153], v[166:169], v[124:127]
	v_mfma_f32_16x16x32_bf16 v[120:123], v[158:161], v[166:169], v[120:123]
	v_mfma_f32_16x16x32_bf16 v[116:119], v[150:153], v[174:177], v[116:119]
	v_mfma_f32_16x16x32_bf16 v[112:115], v[158:161], v[174:177], v[112:115]
	v_mfma_f32_16x16x32_bf16 v[100:103], v[150:153], v[182:185], v[100:103]
	v_mfma_f32_16x16x32_bf16 v[96:99], v[158:161], v[182:185], v[96:99]
	v_mfma_f32_16x16x32_bf16 v[84:87], v[150:153], v[190:193], v[84:87]
	v_mfma_f32_16x16x32_bf16 v[80:83], v[158:161], v[190:193], v[80:83]
	v_mfma_f32_16x16x32_bf16 v[124:127], v[154:157], v[170:173], v[124:127]
	v_mfma_f32_16x16x32_bf16 v[120:123], v[162:165], v[170:173], v[120:123]
	v_mfma_f32_16x16x32_bf16 v[116:119], v[154:157], v[178:181], v[116:119]
	v_mfma_f32_16x16x32_bf16 v[112:115], v[162:165], v[178:181], v[112:115]
	v_mfma_f32_16x16x32_bf16 v[100:103], v[154:157], v[186:189], v[100:103]
	v_mfma_f32_16x16x32_bf16 v[96:99], v[162:165], v[186:189], v[96:99]
	v_mfma_f32_16x16x32_bf16 v[84:87], v[154:157], v[194:197], v[84:87]
	v_mfma_f32_16x16x32_bf16 v[80:83], v[162:165], v[194:197], v[80:83]
	s_setprio 0
	s_barrier
	s_add_i32 s14, s35, s23
	v_lshl_add_u64 v[206:207], s[18:19], 0, v[130:131]
	s_mov_b32 m0, s14
	ds_read_b128 v[198:201], v149
	ds_read_b128 v[202:205], v149 offset:1024
	ds_read_b128 v[210:213], v149 offset:2048
	ds_read_b128 v[214:217], v149 offset:3072
	global_load_lds_dwordx4 v[206:207], off
	v_lshl_add_u64 v[218:219], s[18:19], 0, v[134:135]
	s_add_i32 m0, s14, 0x2000
	s_nop 0
	global_load_lds_dwordx4 v[218:219], off
	s_waitcnt vmcnt(10)
	s_barrier
	s_waitcnt lgkmcnt(0)
	s_setprio 1
	s_waitcnt lgkmcnt(0)
	v_mfma_f32_16x16x32_bf16 v[108:111], v[198:201], v[166:169], v[108:111]
	v_mfma_f32_16x16x32_bf16 v[104:107], v[210:213], v[166:169], v[104:107]
	v_mfma_f32_16x16x32_bf16 v[92:95], v[198:201], v[174:177], v[92:95]
	v_mfma_f32_16x16x32_bf16 v[88:91], v[210:213], v[174:177], v[88:91]
	v_mfma_f32_16x16x32_bf16 v[76:79], v[198:201], v[182:185], v[76:79]
	v_mfma_f32_16x16x32_bf16 v[72:75], v[210:213], v[182:185], v[72:75]
	v_mfma_f32_16x16x32_bf16 v[68:71], v[198:201], v[190:193], v[68:71]
	v_mfma_f32_16x16x32_bf16 v[64:67], v[210:213], v[190:193], v[64:67]
	v_mfma_f32_16x16x32_bf16 v[108:111], v[202:205], v[170:173], v[108:111]
	v_mfma_f32_16x16x32_bf16 v[104:107], v[214:217], v[170:173], v[104:107]
	v_mfma_f32_16x16x32_bf16 v[92:95], v[202:205], v[178:181], v[92:95]
	v_mfma_f32_16x16x32_bf16 v[88:91], v[214:217], v[178:181], v[88:91]
	v_mfma_f32_16x16x32_bf16 v[76:79], v[202:205], v[186:189], v[76:79]
	v_mfma_f32_16x16x32_bf16 v[72:75], v[214:217], v[186:189], v[72:75]
	v_mfma_f32_16x16x32_bf16 v[68:71], v[202:205], v[194:197], v[68:71]
	v_mfma_f32_16x16x32_bf16 v[64:67], v[214:217], v[194:197], v[64:67]
	s_setprio 0
	s_mov_b32 m0, s24
	v_lshl_add_u64 v[220:221], s[20:21], 0, v[128:129]
	s_barrier
	ds_read_b128 v[166:169], v148 offset:16384
	ds_read_b128 v[170:173], v148 offset:17408
	ds_read_b128 v[174:177], v148 offset:18432
	ds_read_b128 v[178:181], v148 offset:19456
	ds_read_b128 v[182:185], v148 offset:20480
	ds_read_b128 v[186:189], v148 offset:21504
	ds_read_b128 v[190:193], v148 offset:22528
	ds_read_b128 v[194:197], v148 offset:23552
	global_load_lds_dwordx4 v[220:221], off
	v_lshl_add_u64 v[222:223], s[20:21], 0, v[132:133]
	s_mov_b32 m0, s25
	s_nop 0
	global_load_lds_dwordx4 v[222:223], off
	s_waitcnt vmcnt(10)
	s_barrier
	s_waitcnt lgkmcnt(0)
	s_setprio 1
	s_waitcnt lgkmcnt(0)
	v_mfma_f32_16x16x32_bf16 v[60:63], v[150:153], v[166:169], v[60:63]
	v_mfma_f32_16x16x32_bf16 v[56:59], v[158:161], v[166:169], v[56:59]
	v_mfma_f32_16x16x32_bf16 v[52:55], v[150:153], v[174:177], v[52:55]
	v_mfma_f32_16x16x32_bf16 v[48:51], v[158:161], v[174:177], v[48:51]
	v_mfma_f32_16x16x32_bf16 v[36:39], v[150:153], v[182:185], v[36:39]
	v_mfma_f32_16x16x32_bf16 v[32:35], v[158:161], v[182:185], v[32:35]
	v_mfma_f32_16x16x32_bf16 v[20:23], v[150:153], v[190:193], v[20:23]
	v_mfma_f32_16x16x32_bf16 v[16:19], v[158:161], v[190:193], v[16:19]
	v_mfma_f32_16x16x32_bf16 v[60:63], v[154:157], v[170:173], v[60:63]
	v_mfma_f32_16x16x32_bf16 v[56:59], v[162:165], v[170:173], v[56:59]
	v_mfma_f32_16x16x32_bf16 v[52:55], v[154:157], v[178:181], v[52:55]
	v_mfma_f32_16x16x32_bf16 v[48:51], v[162:165], v[178:181], v[48:51]
	v_mfma_f32_16x16x32_bf16 v[36:39], v[154:157], v[186:189], v[36:39]
	v_mfma_f32_16x16x32_bf16 v[32:35], v[162:165], v[186:189], v[32:35]
	v_mfma_f32_16x16x32_bf16 v[20:23], v[154:157], v[194:197], v[20:23]
	v_mfma_f32_16x16x32_bf16 v[16:19], v[162:165], v[194:197], v[16:19]
	s_setprio 0
	s_barrier
	s_add_u32 s14, s18, 0xe0000
	s_addc_u32 s15, s19, 0
	s_add_i32 s45, s36, s23
	v_lshl_add_u64 v[150:151], s[14:15], 0, v[130:131]
	s_mov_b32 m0, s45
	s_nop 0
	global_load_lds_dwordx4 v[150:151], off
	v_lshl_add_u64 v[150:151], s[14:15], 0, v[134:135]
	s_add_i32 m0, s45, 0x2000
	s_nop 0
	global_load_lds_dwordx4 v[150:151], off
	s_waitcnt vmcnt(10)
	s_barrier
	s_setprio 1
	v_mfma_f32_16x16x32_bf16 v[44:47], v[198:201], v[166:169], v[44:47]
	v_mfma_f32_16x16x32_bf16 v[40:43], v[210:213], v[166:169], v[40:43]
	v_mfma_f32_16x16x32_bf16 v[28:31], v[198:201], v[174:177], v[28:31]
	v_mfma_f32_16x16x32_bf16 v[24:27], v[210:213], v[174:177], v[24:27]
	v_mfma_f32_16x16x32_bf16 v[12:15], v[198:201], v[182:185], v[12:15]
	v_mfma_f32_16x16x32_bf16 v[8:11], v[210:213], v[182:185], v[8:11]
	v_mfma_f32_16x16x32_bf16 v[4:7], v[198:201], v[190:193], v[4:7]
	v_mfma_f32_16x16x32_bf16 v[0:3], v[210:213], v[190:193], v[0:3]
	v_mfma_f32_16x16x32_bf16 v[44:47], v[202:205], v[170:173], v[44:47]
	v_mfma_f32_16x16x32_bf16 v[40:43], v[214:217], v[170:173], v[40:43]
	v_mfma_f32_16x16x32_bf16 v[28:31], v[202:205], v[178:181], v[28:31]
	v_mfma_f32_16x16x32_bf16 v[24:27], v[214:217], v[178:181], v[24:27]
	v_mfma_f32_16x16x32_bf16 v[12:15], v[202:205], v[186:189], v[12:15]
	v_mfma_f32_16x16x32_bf16 v[8:11], v[214:217], v[186:189], v[8:11]
	v_mfma_f32_16x16x32_bf16 v[4:7], v[202:205], v[194:197], v[4:7]
	v_mfma_f32_16x16x32_bf16 v[0:3], v[214:217], v[194:197], v[0:3]
	s_setprio 0
	s_add_i32 s45, 0, 0x18000
	v_add_u32_e32 v162, s45, v146
	s_barrier
	ds_read_b128 v[150:153], v162
	ds_read_b128 v[154:157], v162 offset:1024
	ds_read_b128 v[158:161], v162 offset:2048
	ds_read_b128 v[162:165], v162 offset:3072
	s_add_u32 s14, s20, 0xe0000
	s_addc_u32 s15, s21, 0
	s_mov_b32 m0, s26
	v_lshl_add_u64 v[198:199], s[14:15], 0, v[128:129]
	ds_read_b128 v[166:169], v148 offset:32768
	ds_read_b128 v[170:173], v148 offset:33792
	ds_read_b128 v[174:177], v148 offset:34816
	ds_read_b128 v[178:181], v148 offset:35840
	ds_read_b128 v[182:185], v148 offset:36864
	ds_read_b128 v[186:189], v148 offset:37888
	ds_read_b128 v[190:193], v148 offset:38912
	ds_read_b128 v[194:197], v148 offset:39936
	global_load_lds_dwordx4 v[198:199], off
	v_lshl_add_u64 v[198:199], s[14:15], 0, v[132:133]
	s_mov_b32 m0, s27
	s_nop 0
	global_load_lds_dwordx4 v[198:199], off
	s_waitcnt lgkmcnt(8)
	s_waitcnt vmcnt(10)
	s_barrier
	s_waitcnt lgkmcnt(0)
	s_setprio 1
	s_waitcnt lgkmcnt(0)
	v_mfma_f32_16x16x32_bf16 v[124:127], v[150:153], v[166:169], v[124:127]
	v_mfma_f32_16x16x32_bf16 v[120:123], v[158:161], v[166:169], v[120:123]
	v_mfma_f32_16x16x32_bf16 v[116:119], v[150:153], v[174:177], v[116:119]
	v_mfma_f32_16x16x32_bf16 v[112:115], v[158:161], v[174:177], v[112:115]
	v_mfma_f32_16x16x32_bf16 v[100:103], v[150:153], v[182:185], v[100:103]
	v_mfma_f32_16x16x32_bf16 v[96:99], v[158:161], v[182:185], v[96:99]
	v_mfma_f32_16x16x32_bf16 v[84:87], v[150:153], v[190:193], v[84:87]
	v_mfma_f32_16x16x32_bf16 v[80:83], v[158:161], v[190:193], v[80:83]
	v_mfma_f32_16x16x32_bf16 v[124:127], v[154:157], v[170:173], v[124:127]
	v_mfma_f32_16x16x32_bf16 v[120:123], v[162:165], v[170:173], v[120:123]
	v_mfma_f32_16x16x32_bf16 v[116:119], v[154:157], v[178:181], v[116:119]
	v_mfma_f32_16x16x32_bf16 v[112:115], v[162:165], v[178:181], v[112:115]
	v_mfma_f32_16x16x32_bf16 v[100:103], v[154:157], v[186:189], v[100:103]
	v_mfma_f32_16x16x32_bf16 v[96:99], v[162:165], v[186:189], v[96:99]
	v_mfma_f32_16x16x32_bf16 v[84:87], v[154:157], v[194:197], v[84:87]
	v_mfma_f32_16x16x32_bf16 v[80:83], v[162:165], v[194:197], v[80:83]
	s_setprio 0
	s_barrier
	s_add_i32 s20, 0, 0x1c000
	s_add_i32 s14, s45, s23
	v_add_u32_e32 v214, s20, v146
	v_lshl_add_u64 v[206:207], v[206:207], 0, s[8:9]
	s_mov_b32 m0, s14
	ds_read_b128 v[198:201], v214
	ds_read_b128 v[202:205], v214 offset:1024
	ds_read_b128 v[210:213], v214 offset:2048
	ds_read_b128 v[214:217], v214 offset:3072
	global_load_lds_dwordx4 v[206:207], off
	v_lshl_add_u64 v[206:207], v[218:219], 0, s[8:9]
	s_add_i32 m0, s14, 0x2000
	s_nop 0
	global_load_lds_dwordx4 v[206:207], off
	s_waitcnt vmcnt(10)
	s_barrier
	s_waitcnt lgkmcnt(0)
	s_setprio 1
	s_waitcnt lgkmcnt(0)
	v_mfma_f32_16x16x32_bf16 v[108:111], v[198:201], v[166:169], v[108:111]
	v_mfma_f32_16x16x32_bf16 v[104:107], v[210:213], v[166:169], v[104:107]
	v_mfma_f32_16x16x32_bf16 v[92:95], v[198:201], v[174:177], v[92:95]
	v_mfma_f32_16x16x32_bf16 v[88:91], v[210:213], v[174:177], v[88:91]
	v_mfma_f32_16x16x32_bf16 v[76:79], v[198:201], v[182:185], v[76:79]
	v_mfma_f32_16x16x32_bf16 v[72:75], v[210:213], v[182:185], v[72:75]
	v_mfma_f32_16x16x32_bf16 v[68:71], v[198:201], v[190:193], v[68:71]
	v_mfma_f32_16x16x32_bf16 v[64:67], v[210:213], v[190:193], v[64:67]
	v_mfma_f32_16x16x32_bf16 v[108:111], v[202:205], v[170:173], v[108:111]
	v_mfma_f32_16x16x32_bf16 v[104:107], v[214:217], v[170:173], v[104:107]
	v_mfma_f32_16x16x32_bf16 v[92:95], v[202:205], v[178:181], v[92:95]
	v_mfma_f32_16x16x32_bf16 v[88:91], v[214:217], v[178:181], v[88:91]
	v_mfma_f32_16x16x32_bf16 v[76:79], v[202:205], v[186:189], v[76:79]
	v_mfma_f32_16x16x32_bf16 v[72:75], v[214:217], v[186:189], v[72:75]
	v_mfma_f32_16x16x32_bf16 v[68:71], v[202:205], v[194:197], v[68:71]
	v_mfma_f32_16x16x32_bf16 v[64:67], v[214:217], v[194:197], v[64:67]
	s_setprio 0
	s_mov_b32 m0, s31
	v_lshl_add_u64 v[206:207], v[220:221], 0, s[8:9]
	s_barrier
	ds_read_b128 v[166:169], v148 offset:49152
	ds_read_b128 v[170:173], v148 offset:50176
	ds_read_b128 v[174:177], v148 offset:51200
	ds_read_b128 v[178:181], v148 offset:52224
	ds_read_b128 v[182:185], v148 offset:53248
	ds_read_b128 v[186:189], v148 offset:54272
	ds_read_b128 v[190:193], v148 offset:55296
	ds_read_b128 v[194:197], v148 offset:56320
	global_load_lds_dwordx4 v[206:207], off
	v_lshl_add_u64 v[206:207], v[222:223], 0, s[8:9]
	s_mov_b32 m0, s33
	s_nop 0
	global_load_lds_dwordx4 v[206:207], off
	s_waitcnt vmcnt(10)
	s_barrier
	s_waitcnt lgkmcnt(0)
	s_setprio 1
	s_waitcnt lgkmcnt(0)
	v_mfma_f32_16x16x32_bf16 v[60:63], v[150:153], v[166:169], v[60:63]
	v_mfma_f32_16x16x32_bf16 v[56:59], v[158:161], v[166:169], v[56:59]
	v_mfma_f32_16x16x32_bf16 v[52:55], v[150:153], v[174:177], v[52:55]
	v_mfma_f32_16x16x32_bf16 v[48:51], v[158:161], v[174:177], v[48:51]
	v_mfma_f32_16x16x32_bf16 v[36:39], v[150:153], v[182:185], v[36:39]
	v_mfma_f32_16x16x32_bf16 v[32:35], v[158:161], v[182:185], v[32:35]
	v_mfma_f32_16x16x32_bf16 v[20:23], v[150:153], v[190:193], v[20:23]
	v_mfma_f32_16x16x32_bf16 v[16:19], v[158:161], v[190:193], v[16:19]
	v_mfma_f32_16x16x32_bf16 v[60:63], v[154:157], v[170:173], v[60:63]
	v_mfma_f32_16x16x32_bf16 v[56:59], v[162:165], v[170:173], v[56:59]
	v_mfma_f32_16x16x32_bf16 v[52:55], v[154:157], v[178:181], v[52:55]
	v_mfma_f32_16x16x32_bf16 v[48:51], v[162:165], v[178:181], v[48:51]
	v_mfma_f32_16x16x32_bf16 v[36:39], v[154:157], v[186:189], v[36:39]
	v_mfma_f32_16x16x32_bf16 v[32:35], v[162:165], v[186:189], v[32:35]
	v_mfma_f32_16x16x32_bf16 v[20:23], v[154:157], v[194:197], v[20:23]
	v_mfma_f32_16x16x32_bf16 v[16:19], v[162:165], v[194:197], v[16:19]
	s_setprio 0
	s_barrier
	s_add_u32 s14, s18, 0xe0080
	s_addc_u32 s15, s19, 0
	s_add_i32 s18, s20, s23
	v_lshl_add_u64 v[150:151], s[14:15], 0, v[130:131]
	s_mov_b32 m0, s18
	s_nop 0
	global_load_lds_dwordx4 v[150:151], off
	v_lshl_add_u64 v[150:151], s[14:15], 0, v[134:135]
	s_add_i32 m0, s18, 0x2000
	s_nop 0
	global_load_lds_dwordx4 v[150:151], off
	s_waitcnt vmcnt(10)
	s_barrier
	s_setprio 1
	v_mfma_f32_16x16x32_bf16 v[44:47], v[198:201], v[166:169], v[44:47]
	v_mfma_f32_16x16x32_bf16 v[40:43], v[210:213], v[166:169], v[40:43]
	v_mfma_f32_16x16x32_bf16 v[28:31], v[198:201], v[174:177], v[28:31]
	v_mfma_f32_16x16x32_bf16 v[24:27], v[210:213], v[174:177], v[24:27]
	v_mfma_f32_16x16x32_bf16 v[12:15], v[198:201], v[182:185], v[12:15]
	v_mfma_f32_16x16x32_bf16 v[8:11], v[210:213], v[182:185], v[8:11]
	v_mfma_f32_16x16x32_bf16 v[4:7], v[198:201], v[190:193], v[4:7]
	v_mfma_f32_16x16x32_bf16 v[0:3], v[210:213], v[190:193], v[0:3]
	v_mfma_f32_16x16x32_bf16 v[44:47], v[202:205], v[170:173], v[44:47]
	v_mfma_f32_16x16x32_bf16 v[40:43], v[214:217], v[170:173], v[40:43]
	v_mfma_f32_16x16x32_bf16 v[28:31], v[202:205], v[178:181], v[28:31]
	v_mfma_f32_16x16x32_bf16 v[24:27], v[214:217], v[178:181], v[24:27]
	v_mfma_f32_16x16x32_bf16 v[12:15], v[202:205], v[186:189], v[12:15]
	v_mfma_f32_16x16x32_bf16 v[8:11], v[214:217], v[186:189], v[8:11]
	v_mfma_f32_16x16x32_bf16 v[4:7], v[202:205], v[194:197], v[4:7]
	v_mfma_f32_16x16x32_bf16 v[0:3], v[214:217], v[194:197], v[0:3]
	s_setprio 0
	s_add_i32 s44, s44, 2
	s_add_u32 s42, s42, 0x100
	s_addc_u32 s43, s43, 0
	s_cmp_gt_u32 s44, 53
	s_mov_b64 s[14:15], s[16:17]
	s_barrier
	s_cbranch_scc0 .LBB0_974
	v_mov_b32_e32 v150, v145
	v_mov_b32_e32 v151, v144
	s_lshl_b32 s14, s34, 8
	s_add_i32 s14, s14, s29
	v_add_u32_e32 v150, s14, v150
	s_lshl_b32 s14, s41, 8
	s_or_b32 s14, s14, s30
	v_lshl_add_u32 v152, v151, 3, s14
	v_ashrrev_i32_e32 v151, 31, v150
	v_lshlrev_b64 v[150:151], 12, v[150:151]
	v_ashrrev_i32_e32 v153, 31, v152
	v_lshl_add_u64 v[150:151], s[10:11], 0, v[150:151]
	v_lshl_add_u64 v[150:151], v[152:153], 1, v[150:151]
	v_cvt_pk_bf16_f32 v108, v108, v109
	v_cvt_pk_bf16_f32 v109, v110, v111
	v_cvt_pk_bf16_f32 v110, v104, v105
	v_cvt_pk_bf16_f32 v111, v106, v107
	s_mov_b64 s[14:15], 0x10000
	global_store_dwordx4 v[150:151], v[108:111], off offset:256
	v_cvt_pk_bf16_f32 v92, v92, v93
	v_cvt_pk_bf16_f32 v93, v94, v95
	v_lshl_add_u64 v[108:109], v[150:151], 0, s[14:15]
	s_mov_b32 s14, 0x10000
	v_add_co_u32_e32 v110, vcc, s14, v150
	v_cvt_pk_bf16_f32 v94, v88, v89
	v_cvt_pk_bf16_f32 v95, v90, v91
	s_mov_b64 s[14:15], 0x20000
	v_addc_co_u32_e32 v111, vcc, 0, v151, vcc
	global_store_dwordx4 v[108:109], v[92:95], off offset:256
	v_cvt_pk_bf16_f32 v76, v76, v77
	v_cvt_pk_bf16_f32 v77, v78, v79
	v_lshl_add_u64 v[92:93], v[150:151], 0, s[14:15]
	s_mov_b32 s14, 0x20000
	v_add_co_u32_e32 v94, vcc, s14, v150
	v_cvt_pk_bf16_f32 v78, v72, v73
	v_cvt_pk_bf16_f32 v79, v74, v75
	s_mov_b64 s[14:15], 0x30000
	v_addc_co_u32_e32 v95, vcc, 0, v151, vcc
	global_store_dwordx4 v[92:93], v[76:79], off offset:256
	v_cvt_pk_bf16_f32 v68, v68, v69
	v_cvt_pk_bf16_f32 v69, v70, v71
	v_lshl_add_u64 v[76:77], v[150:151], 0, s[14:15]
	s_mov_b32 s14, 0x30000
	v_add_co_u32_e32 v78, vcc, s14, v150
	s_mov_b64 s[14:15], 0x80000
	s_nop 0
	v_addc_co_u32_e32 v79, vcc, 0, v151, vcc
	v_cvt_pk_bf16_f32 v70, v64, v65
	v_lshl_add_u64 v[64:65], v[150:151], 0, s[14:15]
	s_mov_b32 s14, 0x80000
	v_cvt_pk_bf16_f32 v60, v60, v61
	v_cvt_pk_bf16_f32 v61, v62, v63
	v_cvt_pk_bf16_f32 v62, v56, v57
	v_add_co_u32_e32 v56, vcc, s14, v150
	v_cvt_pk_bf16_f32 v44, v44, v45
	v_cvt_pk_bf16_f32 v45, v46, v47
	v_cvt_pk_bf16_f32 v46, v40, v41
	v_cvt_pk_bf16_f32 v47, v42, v43
	s_mov_b64 s[14:15], 0x90000
	v_addc_co_u32_e32 v57, vcc, 0, v151, vcc
	global_store_dwordx4 v[64:65], v[44:47], off offset:256
	v_cvt_pk_bf16_f32 v28, v28, v29
	v_cvt_pk_bf16_f32 v29, v30, v31
	v_lshl_add_u64 v[44:45], v[150:151], 0, s[14:15]
	s_mov_b32 s14, 0x90000
	v_add_co_u32_e32 v46, vcc, s14, v150
	v_cvt_pk_bf16_f32 v30, v24, v25
	s_nop 0
	v_addc_co_u32_e32 v47, vcc, 0, v151, vcc
	v_cvt_pk_bf16_f32 v31, v26, v27
	global_store_dwordx4 v[44:45], v[28:31], off offset:256
	s_mov_b64 s[14:15], 0xa0000
	v_cvt_pk_bf16_f32 v12, v12, v13
	v_add_co_u32_e32 v30, vcc, s37, v150
	v_lshl_add_u64 v[28:29], v[150:151], 0, s[14:15]
	s_nop 0
	v_addc_co_u32_e32 v31, vcc, 0, v151, vcc
	v_cvt_pk_bf16_f32 v13, v14, v15
	v_cvt_pk_bf16_f32 v14, v8, v9
	v_cvt_pk_bf16_f32 v15, v10, v11
	global_store_dwordx4 v[28:29], v[12:15], off offset:256
	v_cvt_pk_bf16_f32 v124, v124, v125
	v_cvt_pk_bf16_f32 v125, v126, v127
	v_add_co_u32_e32 v14, vcc, s38, v150
	v_cvt_pk_bf16_f32 v126, v120, v121
	s_nop 0
	v_addc_co_u32_e32 v15, vcc, 0, v151, vcc
	v_cvt_pk_bf16_f32 v127, v122, v123
	v_cvt_pk_bf16_f32 v104, v116, v117
	v_cvt_pk_bf16_f32 v105, v118, v119
	v_cvt_pk_bf16_f32 v106, v112, v113
	v_cvt_pk_bf16_f32 v107, v114, v115
	v_cvt_pk_bf16_f32 v88, v100, v101
	v_cvt_pk_bf16_f32 v89, v102, v103
	v_cvt_pk_bf16_f32 v90, v96, v97
	v_cvt_pk_bf16_f32 v91, v98, v99
	v_cvt_pk_bf16_f32 v72, v84, v85
	v_cvt_pk_bf16_f32 v73, v86, v87
	v_cvt_pk_bf16_f32 v74, v80, v81
	v_cvt_pk_bf16_f32 v75, v82, v83
	v_cvt_pk_bf16_f32 v71, v66, v67
	v_cvt_pk_bf16_f32 v63, v58, v59
	v_cvt_pk_bf16_f32 v40, v52, v53
	v_cvt_pk_bf16_f32 v41, v54, v55
	v_cvt_pk_bf16_f32 v42, v48, v49
	v_cvt_pk_bf16_f32 v43, v50, v51
	v_cvt_pk_bf16_f32 v24, v36, v37
	v_cvt_pk_bf16_f32 v25, v38, v39
	v_cvt_pk_bf16_f32 v26, v32, v33
	v_cvt_pk_bf16_f32 v27, v34, v35
	v_lshl_add_u64 v[12:13], v[150:151], 0, s[12:13]
	v_cvt_pk_bf16_f32 v8, v20, v21
	v_cvt_pk_bf16_f32 v9, v22, v23
	v_cvt_pk_bf16_f32 v10, v16, v17
	v_cvt_pk_bf16_f32 v11, v18, v19
	v_cvt_pk_bf16_f32 v4, v4, v5
	v_cvt_pk_bf16_f32 v5, v6, v7
	v_cvt_pk_bf16_f32 v6, v0, v1
	v_cvt_pk_bf16_f32 v7, v2, v3
	s_and_b64 vcc, exec, s[0:1]
	s_mov_b32 s41, s39
	s_mov_b32 s34, s40
	s_mov_b64 s[16:17], s[4:5]
	s_mov_b64 s[14:15], s[2:3]
	global_store_dwordx4 v[150:151], v[124:127], off
	global_store_dwordx4 v[110:111], v[104:107], off
	global_store_dwordx4 v[94:95], v[88:91], off
	global_store_dwordx4 v[78:79], v[72:75], off
	global_store_dwordx4 v[76:77], v[68:71], off offset:256
	global_store_dwordx4 v[56:57], v[60:63], off
	global_store_dwordx4 v[46:47], v[40:43], off
	global_store_dwordx4 v[30:31], v[24:27], off
	global_store_dwordx4 v[14:15], v[8:11], off
	global_store_dwordx4 v[12:13], v[4:7], off offset:256
	s_cbranch_vccz .LBB0_963
	s_waitcnt vmcnt(0)
	s_cmpk_gt_u32 s22, 0xff
	s_cbranch_scc1 .LBB0_978
	s_barrier

.LBB0_1200:
	s_waitcnt lgkmcnt(0)
	ds_read_b128 v[144:147], v151
	ds_read_b128 v[156:159], v151 offset:1024
	ds_read_b128 v[160:163], v151 offset:2048
	ds_read_b128 v[164:167], v151 offset:3072
	s_add_u32 s30, s28, 0xfff80080
	s_addc_u32 s31, s29, -1
	s_cmp_eq_u32 s56, 28
	s_cselect_b32 s35, s4, s31
	s_cselect_b32 s34, s7, s30
	s_cselect_b32 s31, s21, s55
	s_cselect_b32 s30, s23, s54
	v_lshl_add_u64 v[200:201], s[28:29], 0, v[136:137]
	s_add_i32 m0, s17, 0xc000
	ds_read_b128 v[168:171], v152
	ds_read_b128 v[172:175], v152 offset:1024
	ds_read_b128 v[176:179], v152 offset:2048
	ds_read_b128 v[180:183], v152 offset:3072
	ds_read_b128 v[184:187], v152 offset:4096
	ds_read_b128 v[188:191], v152 offset:5120
	ds_read_b128 v[192:195], v152 offset:6144
	ds_read_b128 v[196:199], v152 offset:7168
	global_load_lds_dwordx4 v[200:201], off
	v_lshl_add_u64 v[200:201], s[28:29], 0, v[138:139]
	s_add_i32 m0, s17, 0xe000
	s_nop 0
	global_load_lds_dwordx4 v[200:201], off
	s_waitcnt lgkmcnt(8)
	s_waitcnt vmcnt(10)
	s_barrier
	s_waitcnt lgkmcnt(0)
	s_setprio 1
	s_waitcnt lgkmcnt(0)
	v_mfma_f32_16x16x32_bf16 v[124:127], v[144:147], v[168:171], v[124:127]
	v_mfma_f32_16x16x32_bf16 v[120:123], v[160:163], v[168:171], v[120:123]
	v_mfma_f32_16x16x32_bf16 v[116:119], v[144:147], v[176:179], v[116:119]
	v_mfma_f32_16x16x32_bf16 v[112:115], v[160:163], v[176:179], v[112:115]
	v_mfma_f32_16x16x32_bf16 v[100:103], v[144:147], v[184:187], v[100:103]
	v_mfma_f32_16x16x32_bf16 v[96:99], v[160:163], v[184:187], v[96:99]
	v_mfma_f32_16x16x32_bf16 v[84:87], v[144:147], v[192:195], v[84:87]
	v_mfma_f32_16x16x32_bf16 v[80:83], v[160:163], v[192:195], v[80:83]
	v_mfma_f32_16x16x32_bf16 v[124:127], v[156:159], v[172:175], v[124:127]
	v_mfma_f32_16x16x32_bf16 v[120:123], v[164:167], v[172:175], v[120:123]
	v_mfma_f32_16x16x32_bf16 v[116:119], v[156:159], v[180:183], v[116:119]
	v_mfma_f32_16x16x32_bf16 v[112:115], v[164:167], v[180:183], v[112:115]
	v_mfma_f32_16x16x32_bf16 v[100:103], v[156:159], v[188:191], v[100:103]
	v_mfma_f32_16x16x32_bf16 v[96:99], v[164:167], v[188:191], v[96:99]
	v_mfma_f32_16x16x32_bf16 v[84:87], v[156:159], v[196:199], v[84:87]
	v_mfma_f32_16x16x32_bf16 v[80:83], v[164:167], v[196:199], v[80:83]
	s_setprio 0
	s_barrier
	s_add_i32 s57, s45, s33
	v_lshl_add_u64 v[218:219], s[30:31], 0, v[130:131]
	s_mov_b32 m0, s57
	ds_read_b128 v[200:203], v153
	ds_read_b128 v[204:207], v153 offset:1024
	ds_read_b128 v[210:213], v153 offset:2048
	ds_read_b128 v[214:217], v153 offset:3072
	global_load_lds_dwordx4 v[218:219], off
	v_lshl_add_u64 v[220:221], s[30:31], 0, v[134:135]
	s_add_i32 m0, s57, 0x2000
	s_nop 0
	global_load_lds_dwordx4 v[220:221], off
	s_waitcnt vmcnt(10)
	s_barrier
	s_waitcnt lgkmcnt(0)
	s_setprio 1
	s_waitcnt lgkmcnt(0)
	v_mfma_f32_16x16x32_bf16 v[108:111], v[200:203], v[168:171], v[108:111]
	v_mfma_f32_16x16x32_bf16 v[104:107], v[210:213], v[168:171], v[104:107]
	v_mfma_f32_16x16x32_bf16 v[92:95], v[200:203], v[176:179], v[92:95]
	v_mfma_f32_16x16x32_bf16 v[88:91], v[210:213], v[176:179], v[88:91]
	v_mfma_f32_16x16x32_bf16 v[76:79], v[200:203], v[184:187], v[76:79]
	v_mfma_f32_16x16x32_bf16 v[72:75], v[210:213], v[184:187], v[72:75]
	v_mfma_f32_16x16x32_bf16 v[68:71], v[200:203], v[192:195], v[68:71]
	v_mfma_f32_16x16x32_bf16 v[64:67], v[210:213], v[192:195], v[64:67]
	v_mfma_f32_16x16x32_bf16 v[108:111], v[204:207], v[172:175], v[108:111]
	v_mfma_f32_16x16x32_bf16 v[104:107], v[214:217], v[172:175], v[104:107]
	v_mfma_f32_16x16x32_bf16 v[92:95], v[204:207], v[180:183], v[92:95]
	v_mfma_f32_16x16x32_bf16 v[88:91], v[214:217], v[180:183], v[88:91]
	v_mfma_f32_16x16x32_bf16 v[76:79], v[204:207], v[188:191], v[76:79]
	v_mfma_f32_16x16x32_bf16 v[72:75], v[214:217], v[188:191], v[72:75]
	v_mfma_f32_16x16x32_bf16 v[68:71], v[204:207], v[196:199], v[68:71]
	v_mfma_f32_16x16x32_bf16 v[64:67], v[214:217], v[196:199], v[64:67]
	s_setprio 0
	s_mov_b32 m0, s17
	v_lshl_add_u64 v[222:223], s[34:35], 0, v[128:129]
	s_barrier
	ds_read_b128 v[168:171], v152 offset:16384
	ds_read_b128 v[172:175], v152 offset:17408
	ds_read_b128 v[176:179], v152 offset:18432
	ds_read_b128 v[180:183], v152 offset:19456
	ds_read_b128 v[184:187], v152 offset:20480
	ds_read_b128 v[188:191], v152 offset:21504
	ds_read_b128 v[192:195], v152 offset:22528
	ds_read_b128 v[196:199], v152 offset:23552
	global_load_lds_dwordx4 v[222:223], off
	v_lshl_add_u64 v[224:225], s[34:35], 0, v[132:133]
	s_mov_b32 m0, s38
	s_nop 0
	global_load_lds_dwordx4 v[224:225], off
	s_waitcnt vmcnt(10)
	s_barrier
	s_waitcnt lgkmcnt(0)
	s_setprio 1
	s_waitcnt lgkmcnt(0)
	v_mfma_f32_16x16x32_bf16 v[60:63], v[144:147], v[168:171], v[60:63]
	v_mfma_f32_16x16x32_bf16 v[56:59], v[160:163], v[168:171], v[56:59]
	v_mfma_f32_16x16x32_bf16 v[52:55], v[144:147], v[176:179], v[52:55]
	v_mfma_f32_16x16x32_bf16 v[48:51], v[160:163], v[176:179], v[48:51]
	v_mfma_f32_16x16x32_bf16 v[36:39], v[144:147], v[184:187], v[36:39]
	v_mfma_f32_16x16x32_bf16 v[32:35], v[160:163], v[184:187], v[32:35]
	v_mfma_f32_16x16x32_bf16 v[20:23], v[144:147], v[192:195], v[20:23]
	v_mfma_f32_16x16x32_bf16 v[16:19], v[160:163], v[192:195], v[16:19]
	v_mfma_f32_16x16x32_bf16 v[60:63], v[156:159], v[172:175], v[60:63]
	v_mfma_f32_16x16x32_bf16 v[56:59], v[164:167], v[172:175], v[56:59]
	v_mfma_f32_16x16x32_bf16 v[52:55], v[156:159], v[180:183], v[52:55]
	v_mfma_f32_16x16x32_bf16 v[48:51], v[164:167], v[180:183], v[48:51]
	v_mfma_f32_16x16x32_bf16 v[36:39], v[156:159], v[188:191], v[36:39]
	v_mfma_f32_16x16x32_bf16 v[32:35], v[164:167], v[188:191], v[32:35]
	v_mfma_f32_16x16x32_bf16 v[20:23], v[156:159], v[196:199], v[20:23]
	v_mfma_f32_16x16x32_bf16 v[16:19], v[164:167], v[196:199], v[16:19]
	s_setprio 0
	s_barrier
	s_add_u32 s60, s30, 0x80000
	s_addc_u32 s61, s31, 0
	s_add_i32 s57, s51, s33
	v_lshl_add_u64 v[144:145], s[60:61], 0, v[130:131]
	s_mov_b32 m0, s57
	s_nop 0
	global_load_lds_dwordx4 v[144:145], off
	v_lshl_add_u64 v[144:145], s[60:61], 0, v[134:135]
	s_add_i32 m0, s57, 0x2000
	s_nop 0
	global_load_lds_dwordx4 v[144:145], off
	s_waitcnt vmcnt(10)
	s_barrier
	s_setprio 1
	v_mfma_f32_16x16x32_bf16 v[44:47], v[200:203], v[168:171], v[44:47]
	v_mfma_f32_16x16x32_bf16 v[40:43], v[210:213], v[168:171], v[40:43]
	v_mfma_f32_16x16x32_bf16 v[28:31], v[200:203], v[176:179], v[28:31]
	v_mfma_f32_16x16x32_bf16 v[24:27], v[210:213], v[176:179], v[24:27]
	v_mfma_f32_16x16x32_bf16 v[12:15], v[200:203], v[184:187], v[12:15]
	v_mfma_f32_16x16x32_bf16 v[8:11], v[210:213], v[184:187], v[8:11]
	v_mfma_f32_16x16x32_bf16 v[4:7], v[200:203], v[192:195], v[4:7]
	v_mfma_f32_16x16x32_bf16 v[0:3], v[210:213], v[192:195], v[0:3]
	v_mfma_f32_16x16x32_bf16 v[44:47], v[204:207], v[172:175], v[44:47]
	v_mfma_f32_16x16x32_bf16 v[40:43], v[214:217], v[172:175], v[40:43]
	v_mfma_f32_16x16x32_bf16 v[28:31], v[204:207], v[180:183], v[28:31]
	v_mfma_f32_16x16x32_bf16 v[24:27], v[214:217], v[180:183], v[24:27]
	v_mfma_f32_16x16x32_bf16 v[12:15], v[204:207], v[188:191], v[12:15]
	v_mfma_f32_16x16x32_bf16 v[8:11], v[214:217], v[188:191], v[8:11]
	v_mfma_f32_16x16x32_bf16 v[4:7], v[204:207], v[196:199], v[4:7]
	v_mfma_f32_16x16x32_bf16 v[0:3], v[214:217], v[196:199], v[0:3]
	s_setprio 0
	s_add_i32 s57, 0, 0x18000
	v_add_u32_e32 v155, s57, v150
	s_barrier
	ds_read_b128 v[144:147], v155
	ds_read_b128 v[156:159], v155 offset:1024
	ds_read_b128 v[160:163], v155 offset:2048
	ds_read_b128 v[164:167], v155 offset:3072
	s_add_u32 s34, s34, 0x80000
	s_addc_u32 s35, s35, 0
	s_mov_b32 m0, s39
	v_lshl_add_u64 v[200:201], s[34:35], 0, v[128:129]
	ds_read_b128 v[168:171], v152 offset:32768
	ds_read_b128 v[172:175], v152 offset:33792
	ds_read_b128 v[176:179], v152 offset:34816
	ds_read_b128 v[180:183], v152 offset:35840
	ds_read_b128 v[184:187], v152 offset:36864
	ds_read_b128 v[188:191], v152 offset:37888
	ds_read_b128 v[192:195], v152 offset:38912
	ds_read_b128 v[196:199], v152 offset:39936
	global_load_lds_dwordx4 v[200:201], off
	v_lshl_add_u64 v[200:201], s[34:35], 0, v[132:133]
	s_mov_b32 m0, s40
	s_nop 0
	global_load_lds_dwordx4 v[200:201], off
	s_waitcnt lgkmcnt(8)
	s_waitcnt vmcnt(10)
	s_barrier
	s_waitcnt lgkmcnt(0)
	s_setprio 1
	s_waitcnt lgkmcnt(0)
	v_mfma_f32_16x16x32_bf16 v[124:127], v[144:147], v[168:171], v[124:127]
	v_mfma_f32_16x16x32_bf16 v[120:123], v[160:163], v[168:171], v[120:123]
	v_mfma_f32_16x16x32_bf16 v[116:119], v[144:147], v[176:179], v[116:119]
	v_mfma_f32_16x16x32_bf16 v[112:115], v[160:163], v[176:179], v[112:115]
	v_mfma_f32_16x16x32_bf16 v[100:103], v[144:147], v[184:187], v[100:103]
	v_mfma_f32_16x16x32_bf16 v[96:99], v[160:163], v[184:187], v[96:99]
	v_mfma_f32_16x16x32_bf16 v[84:87], v[144:147], v[192:195], v[84:87]
	v_mfma_f32_16x16x32_bf16 v[80:83], v[160:163], v[192:195], v[80:83]
	v_mfma_f32_16x16x32_bf16 v[124:127], v[156:159], v[172:175], v[124:127]
	v_mfma_f32_16x16x32_bf16 v[120:123], v[164:167], v[172:175], v[120:123]
	v_mfma_f32_16x16x32_bf16 v[116:119], v[156:159], v[180:183], v[116:119]
	v_mfma_f32_16x16x32_bf16 v[112:115], v[164:167], v[180:183], v[112:115]
	v_mfma_f32_16x16x32_bf16 v[100:103], v[156:159], v[188:191], v[100:103]
	v_mfma_f32_16x16x32_bf16 v[96:99], v[164:167], v[188:191], v[96:99]
	v_mfma_f32_16x16x32_bf16 v[84:87], v[156:159], v[196:199], v[84:87]
	v_mfma_f32_16x16x32_bf16 v[80:83], v[164:167], v[196:199], v[80:83]
	s_setprio 0
	s_barrier
	s_add_i32 s34, 0, 0x1c000
	s_add_i32 s35, s57, s33
	v_add_u32_e32 v155, s34, v150
	v_lshl_add_u64 v[218:219], v[218:219], 0, s[8:9]
	s_mov_b32 m0, s35
	ds_read_b128 v[200:203], v155
	ds_read_b128 v[204:207], v155 offset:1024
	ds_read_b128 v[210:213], v155 offset:2048
	ds_read_b128 v[214:217], v155 offset:3072
	global_load_lds_dwordx4 v[218:219], off
	v_lshl_add_u64 v[218:219], v[220:221], 0, s[8:9]
	s_add_i32 m0, s35, 0x2000
	s_nop 0
	global_load_lds_dwordx4 v[218:219], off
	s_waitcnt vmcnt(10)
	s_barrier
	s_waitcnt lgkmcnt(0)
	s_setprio 1
	s_waitcnt lgkmcnt(0)
	v_mfma_f32_16x16x32_bf16 v[108:111], v[200:203], v[168:171], v[108:111]
	v_mfma_f32_16x16x32_bf16 v[104:107], v[210:213], v[168:171], v[104:107]
	v_mfma_f32_16x16x32_bf16 v[92:95], v[200:203], v[176:179], v[92:95]
	v_mfma_f32_16x16x32_bf16 v[88:91], v[210:213], v[176:179], v[88:91]
	v_mfma_f32_16x16x32_bf16 v[76:79], v[200:203], v[184:187], v[76:79]
	v_mfma_f32_16x16x32_bf16 v[72:75], v[210:213], v[184:187], v[72:75]
	v_mfma_f32_16x16x32_bf16 v[68:71], v[200:203], v[192:195], v[68:71]
	v_mfma_f32_16x16x32_bf16 v[64:67], v[210:213], v[192:195], v[64:67]
	v_mfma_f32_16x16x32_bf16 v[108:111], v[204:207], v[172:175], v[108:111]
	v_mfma_f32_16x16x32_bf16 v[104:107], v[214:217], v[172:175], v[104:107]
	v_mfma_f32_16x16x32_bf16 v[92:95], v[204:207], v[180:183], v[92:95]
	v_mfma_f32_16x16x32_bf16 v[88:91], v[214:217], v[180:183], v[88:91]
	v_mfma_f32_16x16x32_bf16 v[76:79], v[204:207], v[188:191], v[76:79]
	v_mfma_f32_16x16x32_bf16 v[72:75], v[214:217], v[188:191], v[72:75]
	v_mfma_f32_16x16x32_bf16 v[68:71], v[204:207], v[196:199], v[68:71]
	v_mfma_f32_16x16x32_bf16 v[64:67], v[214:217], v[196:199], v[64:67]
	s_setprio 0
	s_mov_b32 m0, s43
	v_lshl_add_u64 v[218:219], v[222:223], 0, s[8:9]
	s_barrier
	ds_read_b128 v[168:171], v152 offset:49152
	ds_read_b128 v[172:175], v152 offset:50176
	ds_read_b128 v[176:179], v152 offset:51200
	ds_read_b128 v[180:183], v152 offset:52224
	ds_read_b128 v[184:187], v152 offset:53248
	ds_read_b128 v[188:191], v152 offset:54272
	ds_read_b128 v[192:195], v152 offset:55296
	ds_read_b128 v[196:199], v152 offset:56320
	global_load_lds_dwordx4 v[218:219], off
	v_lshl_add_u64 v[218:219], v[224:225], 0, s[8:9]
	s_mov_b32 m0, s44
	s_nop 0
	global_load_lds_dwordx4 v[218:219], off
	s_waitcnt vmcnt(10)
	s_barrier
	s_waitcnt lgkmcnt(0)
	s_setprio 1
	s_waitcnt lgkmcnt(0)
	v_mfma_f32_16x16x32_bf16 v[60:63], v[144:147], v[168:171], v[60:63]
	v_mfma_f32_16x16x32_bf16 v[56:59], v[160:163], v[168:171], v[56:59]
	v_mfma_f32_16x16x32_bf16 v[52:55], v[144:147], v[176:179], v[52:55]
	v_mfma_f32_16x16x32_bf16 v[48:51], v[160:163], v[176:179], v[48:51]
	v_mfma_f32_16x16x32_bf16 v[36:39], v[144:147], v[184:187], v[36:39]
	v_mfma_f32_16x16x32_bf16 v[32:35], v[160:163], v[184:187], v[32:35]
	v_mfma_f32_16x16x32_bf16 v[20:23], v[144:147], v[192:195], v[20:23]
	v_mfma_f32_16x16x32_bf16 v[16:19], v[160:163], v[192:195], v[16:19]
	v_mfma_f32_16x16x32_bf16 v[60:63], v[156:159], v[172:175], v[60:63]
	v_mfma_f32_16x16x32_bf16 v[56:59], v[164:167], v[172:175], v[56:59]
	v_mfma_f32_16x16x32_bf16 v[52:55], v[156:159], v[180:183], v[52:55]
	v_mfma_f32_16x16x32_bf16 v[48:51], v[164:167], v[180:183], v[48:51]
	v_mfma_f32_16x16x32_bf16 v[36:39], v[156:159], v[188:191], v[36:39]
	v_mfma_f32_16x16x32_bf16 v[32:35], v[164:167], v[188:191], v[32:35]
	v_mfma_f32_16x16x32_bf16 v[20:23], v[156:159], v[196:199], v[20:23]
	v_mfma_f32_16x16x32_bf16 v[16:19], v[164:167], v[196:199], v[16:19]
	s_setprio 0
	s_barrier
	s_add_u32 s30, s30, 0x80080
	s_addc_u32 s31, s31, 0
	s_add_i32 s34, s34, s33
	v_lshl_add_u64 v[144:145], s[30:31], 0, v[130:131]
	s_mov_b32 m0, s34
	s_nop 0
	global_load_lds_dwordx4 v[144:145], off
	v_lshl_add_u64 v[144:145], s[30:31], 0, v[134:135]
	s_add_i32 m0, s34, 0x2000
	s_nop 0
	global_load_lds_dwordx4 v[144:145], off
	s_waitcnt vmcnt(10)
	s_barrier
	s_setprio 1
	v_mfma_f32_16x16x32_bf16 v[44:47], v[200:203], v[168:171], v[44:47]
	v_mfma_f32_16x16x32_bf16 v[40:43], v[210:213], v[168:171], v[40:43]
	v_mfma_f32_16x16x32_bf16 v[28:31], v[200:203], v[176:179], v[28:31]
	v_mfma_f32_16x16x32_bf16 v[24:27], v[210:213], v[176:179], v[24:27]
	v_mfma_f32_16x16x32_bf16 v[12:15], v[200:203], v[184:187], v[12:15]
	v_mfma_f32_16x16x32_bf16 v[8:11], v[210:213], v[184:187], v[8:11]
	v_mfma_f32_16x16x32_bf16 v[4:7], v[200:203], v[192:195], v[4:7]
	v_mfma_f32_16x16x32_bf16 v[0:3], v[210:213], v[192:195], v[0:3]
	v_mfma_f32_16x16x32_bf16 v[44:47], v[204:207], v[172:175], v[44:47]
	v_mfma_f32_16x16x32_bf16 v[40:43], v[214:217], v[172:175], v[40:43]
	v_mfma_f32_16x16x32_bf16 v[28:31], v[204:207], v[180:183], v[28:31]
	v_mfma_f32_16x16x32_bf16 v[24:27], v[214:217], v[180:183], v[24:27]
	v_mfma_f32_16x16x32_bf16 v[12:15], v[204:207], v[188:191], v[12:15]
	v_mfma_f32_16x16x32_bf16 v[8:11], v[214:217], v[188:191], v[8:11]
	v_mfma_f32_16x16x32_bf16 v[4:7], v[204:207], v[196:199], v[4:7]
	v_mfma_f32_16x16x32_bf16 v[0:3], v[214:217], v[196:199], v[0:3]
	s_setprio 0
	s_add_i32 s56, s56, 2
	s_add_u32 s28, s28, 0x100
	s_addc_u32 s29, s29, 0
	s_add_u32 s54, s54, 0x100
	s_addc_u32 s55, s55, 0
	s_cmp_gt_u32 s56, 29
	s_barrier
	s_cbranch_scc0 .LBB0_1200
	v_mov_b32_e32 v155, v148
	v_mov_b32_e32 v156, v149
	s_cmp_gt_i32 s6, 7
	s_mov_b64 s[28:29], -1
	s_cbranch_scc0 .LBB0_1231
	s_cmp_gt_u32 s6, 15
	s_cbranch_scc0 .LBB0_1212
	s_cmp_gt_u32 s6, 23
	s_cbranch_scc0 .LBB0_1209
	s_lshl_b32 s4, s16, 8
	s_add_i32 s4, s4, s41
	v_lshl_add_u32 v144, v156, 3, s42
	v_add_u32_e32 v157, s4, v155
	v_ashrrev_i32_e32 v145, 31, v144
	v_mad_i64_i32 v[146:147], s[28:29], v157, s52, 0
	s_cmp_gt_u32 s6, 25
	s_mov_b64 s[28:29], -1
	v_lshl_add_u64 v[146:147], s[14:15], 0, v[146:147]
	v_lshlrev_b64 v[144:145], 1, v[144:145]
	v_add_u32_e32 v163, 16, v157
	v_add_u32_e32 v162, 32, v157
	v_add_u32_e32 v161, 48, v157
	v_add_u32_e32 v160, 0x80, v157
	v_add_u32_e32 v159, 0x90, v157
	v_add_u32_e32 v158, 0xa0, v157
	v_add_u32_e32 v157, 0xb0, v157
	s_cbranch_scc0 .LBB0_1206
	s_lshl_b32 s4, s6, 9
	v_lshl_add_u64 v[168:169], v[146:147], 0, s[4:5]
	v_cvt_pk_bf16_f32 v164, v124, v125
	v_cvt_pk_bf16_f32 v165, v126, v127
	v_cvt_pk_bf16_f32 v166, v120, v121
	v_cvt_pk_bf16_f32 v167, v122, v123
	v_lshl_add_u64 v[168:169], v[168:169], 0, v[144:145]
	global_store_dwordx4 v[168:169], v[164:167], off
	s_nop 1
	v_cvt_pk_bf16_f32 v164, v108, v109
	v_cvt_pk_bf16_f32 v165, v110, v111
	v_cvt_pk_bf16_f32 v166, v104, v105
	v_cvt_pk_bf16_f32 v167, v106, v107
	global_store_dwordx4 v[168:169], v[164:167], off offset:256
	v_mov_b64_e32 v[168:169], s[14:15]
	v_mad_i64_i32 v[170:171], s[28:29], v163, s52, v[168:169]
	v_lshl_add_u64 v[170:171], v[170:171], 0, s[4:5]
	v_cvt_pk_bf16_f32 v164, v116, v117
	v_cvt_pk_bf16_f32 v165, v118, v119
	v_cvt_pk_bf16_f32 v166, v112, v113
	v_cvt_pk_bf16_f32 v167, v114, v115
	v_lshl_add_u64 v[170:171], v[170:171], 0, v[144:145]
	global_store_dwordx4 v[170:171], v[164:167], off
	s_nop 1
	v_cvt_pk_bf16_f32 v164, v92, v93
	v_cvt_pk_bf16_f32 v165, v94, v95
	v_cvt_pk_bf16_f32 v166, v88, v89
	v_cvt_pk_bf16_f32 v167, v90, v91
	global_store_dwordx4 v[170:171], v[164:167], off offset:256
	v_mad_i64_i32 v[170:171], s[28:29], v162, s52, v[168:169]
	v_lshl_add_u64 v[170:171], v[170:171], 0, s[4:5]
	v_cvt_pk_bf16_f32 v164, v100, v101
	v_cvt_pk_bf16_f32 v165, v102, v103
	v_cvt_pk_bf16_f32 v166, v96, v97
	v_cvt_pk_bf16_f32 v167, v98, v99
	v_lshl_add_u64 v[170:171], v[170:171], 0, v[144:145]
	global_store_dwordx4 v[170:171], v[164:167], off
	s_nop 1
	v_cvt_pk_bf16_f32 v164, v76, v77
	v_cvt_pk_bf16_f32 v165, v78, v79
	v_cvt_pk_bf16_f32 v166, v72, v73
	v_cvt_pk_bf16_f32 v167, v74, v75
	global_store_dwordx4 v[170:171], v[164:167], off offset:256
	v_mad_i64_i32 v[170:171], s[28:29], v161, s52, v[168:169]
	v_lshl_add_u64 v[170:171], v[170:171], 0, s[4:5]
	v_cvt_pk_bf16_f32 v164, v84, v85
	v_cvt_pk_bf16_f32 v165, v86, v87
	v_cvt_pk_bf16_f32 v166, v80, v81
	v_cvt_pk_bf16_f32 v167, v82, v83
	v_lshl_add_u64 v[170:171], v[170:171], 0, v[144:145]
	global_store_dwordx4 v[170:171], v[164:167], off
	s_nop 1
	v_cvt_pk_bf16_f32 v164, v68, v69
	v_cvt_pk_bf16_f32 v165, v70, v71
	v_cvt_pk_bf16_f32 v166, v64, v65
	v_cvt_pk_bf16_f32 v167, v66, v67
	global_store_dwordx4 v[170:171], v[164:167], off offset:256
	v_mad_i64_i32 v[170:171], s[28:29], v160, s52, v[168:169]
	v_lshl_add_u64 v[170:171], v[170:171], 0, s[4:5]
	v_cvt_pk_bf16_f32 v164, v60, v61
	v_cvt_pk_bf16_f32 v165, v62, v63
	v_cvt_pk_bf16_f32 v166, v56, v57
	v_cvt_pk_bf16_f32 v167, v58, v59
	v_lshl_add_u64 v[170:171], v[170:171], 0, v[144:145]
	global_store_dwordx4 v[170:171], v[164:167], off
	s_nop 1
	v_cvt_pk_bf16_f32 v164, v44, v45
	v_cvt_pk_bf16_f32 v165, v46, v47
	v_cvt_pk_bf16_f32 v166, v40, v41
	v_cvt_pk_bf16_f32 v167, v42, v43
	global_store_dwordx4 v[170:171], v[164:167], off offset:256
	v_mad_i64_i32 v[170:171], s[28:29], v159, s52, v[168:169]
	v_lshl_add_u64 v[170:171], v[170:171], 0, s[4:5]
	v_cvt_pk_bf16_f32 v164, v52, v53
	v_cvt_pk_bf16_f32 v165, v54, v55
	v_cvt_pk_bf16_f32 v166, v48, v49
	v_cvt_pk_bf16_f32 v167, v50, v51
	v_lshl_add_u64 v[170:171], v[170:171], 0, v[144:145]
	global_store_dwordx4 v[170:171], v[164:167], off
	s_nop 1
	v_cvt_pk_bf16_f32 v164, v28, v29
	v_cvt_pk_bf16_f32 v165, v30, v31
	v_cvt_pk_bf16_f32 v166, v24, v25
	v_cvt_pk_bf16_f32 v167, v26, v27
	global_store_dwordx4 v[170:171], v[164:167], off offset:256
	v_mad_i64_i32 v[170:171], s[28:29], v158, s52, v[168:169]
	v_lshl_add_u64 v[170:171], v[170:171], 0, s[4:5]
	v_cvt_pk_bf16_f32 v164, v36, v37
	v_cvt_pk_bf16_f32 v165, v38, v39
	v_cvt_pk_bf16_f32 v166, v32, v33
	v_cvt_pk_bf16_f32 v167, v34, v35
	v_lshl_add_u64 v[170:171], v[170:171], 0, v[144:145]
	v_mad_i64_i32 v[168:169], s[28:29], v157, s52, v[168:169]
	global_store_dwordx4 v[170:171], v[164:167], off
	v_lshl_add_u64 v[168:169], v[168:169], 0, s[4:5]
	v_lshl_add_u64 v[168:169], v[168:169], 0, v[144:145]
	v_cvt_pk_bf16_f32 v164, v12, v13
	v_cvt_pk_bf16_f32 v165, v14, v15
	v_cvt_pk_bf16_f32 v166, v8, v9
	v_cvt_pk_bf16_f32 v167, v10, v11
	global_store_dwordx4 v[170:171], v[164:167], off offset:256
	s_mov_b64 s[28:29], 0
	s_nop 0
	v_cvt_pk_bf16_f32 v164, v20, v21
	v_cvt_pk_bf16_f32 v165, v22, v23
	v_cvt_pk_bf16_f32 v166, v16, v17
	v_cvt_pk_bf16_f32 v167, v18, v19
	global_store_dwordx4 v[168:169], v[164:167], off
	s_nop 1
	v_cvt_pk_bf16_f32 v164, v4, v5
	v_cvt_pk_bf16_f32 v165, v6, v7
	v_cvt_pk_bf16_f32 v166, v0, v1
	v_cvt_pk_bf16_f32 v167, v2, v3
	global_store_dwordx4 v[168:169], v[164:167], off offset:256

.LBB0_1402:
	ds_read_b128 v[150:153], v147
	ds_read_b128 v[154:157], v147 offset:1024
	ds_read_b128 v[158:161], v147 offset:2048
	ds_read_b128 v[162:165], v147 offset:3072
	s_add_u32 s34, s30, 0x100
	s_addc_u32 s35, s31, 0
	s_cmp_eq_u32 s69, 36
	s_cselect_b32 s39, s5, s35
	s_cselect_b32 s38, s4, s34
	s_cselect_b32 s37, s7, s68
	s_cselect_b32 s36, s6, s67
	v_lshl_add_u64 v[198:199], s[30:31], 0, v[136:137]
	s_add_i32 m0, s41, 0xc000
	ds_read_b128 v[166:169], v148
	ds_read_b128 v[170:173], v148 offset:1024
	ds_read_b128 v[174:177], v148 offset:2048
	ds_read_b128 v[178:181], v148 offset:3072
	ds_read_b128 v[182:185], v148 offset:4096
	ds_read_b128 v[186:189], v148 offset:5120
	ds_read_b128 v[190:193], v148 offset:6144
	ds_read_b128 v[194:197], v148 offset:7168
	global_load_lds_dwordx4 v[198:199], off
	v_lshl_add_u64 v[198:199], s[30:31], 0, v[138:139]
	s_add_i32 m0, s41, 0xe000
	s_nop 0
	global_load_lds_dwordx4 v[198:199], off
	s_waitcnt lgkmcnt(8)
	s_waitcnt vmcnt(10)
	s_barrier
	s_waitcnt lgkmcnt(0)
	s_setprio 1
	s_waitcnt lgkmcnt(0)
	v_mfma_f32_16x16x32_bf16 v[124:127], v[150:153], v[166:169], v[124:127]
	v_mfma_f32_16x16x32_bf16 v[120:123], v[158:161], v[166:169], v[120:123]
	v_mfma_f32_16x16x32_bf16 v[116:119], v[150:153], v[174:177], v[116:119]
	v_mfma_f32_16x16x32_bf16 v[112:115], v[158:161], v[174:177], v[112:115]
	v_mfma_f32_16x16x32_bf16 v[100:103], v[150:153], v[182:185], v[100:103]
	v_mfma_f32_16x16x32_bf16 v[96:99], v[158:161], v[182:185], v[96:99]
	v_mfma_f32_16x16x32_bf16 v[84:87], v[150:153], v[190:193], v[84:87]
	v_mfma_f32_16x16x32_bf16 v[80:83], v[158:161], v[190:193], v[80:83]
	v_mfma_f32_16x16x32_bf16 v[124:127], v[154:157], v[170:173], v[124:127]
	v_mfma_f32_16x16x32_bf16 v[120:123], v[162:165], v[170:173], v[120:123]
	v_mfma_f32_16x16x32_bf16 v[116:119], v[154:157], v[178:181], v[116:119]
	v_mfma_f32_16x16x32_bf16 v[112:115], v[162:165], v[178:181], v[112:115]
	v_mfma_f32_16x16x32_bf16 v[100:103], v[154:157], v[186:189], v[100:103]
	v_mfma_f32_16x16x32_bf16 v[96:99], v[162:165], v[186:189], v[96:99]
	v_mfma_f32_16x16x32_bf16 v[84:87], v[154:157], v[194:197], v[84:87]
	v_mfma_f32_16x16x32_bf16 v[80:83], v[162:165], v[194:197], v[80:83]
	s_setprio 0
	s_barrier
	s_add_i32 s30, s54, s40
	v_lshl_add_u64 v[206:207], s[36:37], 0, v[130:131]
	s_mov_b32 m0, s30
	ds_read_b128 v[198:201], v149
	ds_read_b128 v[202:205], v149 offset:1024
	ds_read_b128 v[210:213], v149 offset:2048
	ds_read_b128 v[214:217], v149 offset:3072
	global_load_lds_dwordx4 v[206:207], off
	v_lshl_add_u64 v[218:219], s[36:37], 0, v[134:135]
	s_add_i32 m0, s30, 0x2000
	s_nop 0
	global_load_lds_dwordx4 v[218:219], off
	s_waitcnt vmcnt(10)
	s_barrier
	s_waitcnt lgkmcnt(0)
	s_setprio 1
	s_waitcnt lgkmcnt(0)
	v_mfma_f32_16x16x32_bf16 v[108:111], v[198:201], v[166:169], v[108:111]
	v_mfma_f32_16x16x32_bf16 v[104:107], v[210:213], v[166:169], v[104:107]
	v_mfma_f32_16x16x32_bf16 v[92:95], v[198:201], v[174:177], v[92:95]
	v_mfma_f32_16x16x32_bf16 v[88:91], v[210:213], v[174:177], v[88:91]
	v_mfma_f32_16x16x32_bf16 v[76:79], v[198:201], v[182:185], v[76:79]
	v_mfma_f32_16x16x32_bf16 v[72:75], v[210:213], v[182:185], v[72:75]
	v_mfma_f32_16x16x32_bf16 v[68:71], v[198:201], v[190:193], v[68:71]
	v_mfma_f32_16x16x32_bf16 v[64:67], v[210:213], v[190:193], v[64:67]
	v_mfma_f32_16x16x32_bf16 v[108:111], v[202:205], v[170:173], v[108:111]
	v_mfma_f32_16x16x32_bf16 v[104:107], v[214:217], v[170:173], v[104:107]
	v_mfma_f32_16x16x32_bf16 v[92:95], v[202:205], v[178:181], v[92:95]
	v_mfma_f32_16x16x32_bf16 v[88:91], v[214:217], v[178:181], v[88:91]
	v_mfma_f32_16x16x32_bf16 v[76:79], v[202:205], v[186:189], v[76:79]
	v_mfma_f32_16x16x32_bf16 v[72:75], v[214:217], v[186:189], v[72:75]
	v_mfma_f32_16x16x32_bf16 v[68:71], v[202:205], v[194:197], v[68:71]
	v_mfma_f32_16x16x32_bf16 v[64:67], v[214:217], v[194:197], v[64:67]
	s_setprio 0
	s_mov_b32 m0, s41
	v_lshl_add_u64 v[220:221], s[38:39], 0, v[128:129]
	s_barrier
	ds_read_b128 v[166:169], v148 offset:16384
	ds_read_b128 v[170:173], v148 offset:17408
	ds_read_b128 v[174:177], v148 offset:18432
	ds_read_b128 v[178:181], v148 offset:19456
	ds_read_b128 v[182:185], v148 offset:20480
	ds_read_b128 v[186:189], v148 offset:21504
	ds_read_b128 v[190:193], v148 offset:22528
	ds_read_b128 v[194:197], v148 offset:23552
	global_load_lds_dwordx4 v[220:221], off
	v_lshl_add_u64 v[222:223], s[38:39], 0, v[132:133]
	s_mov_b32 m0, s42
	s_nop 0
	global_load_lds_dwordx4 v[222:223], off
	s_waitcnt vmcnt(10)
	s_barrier
	s_waitcnt lgkmcnt(0)
	s_setprio 1
	s_waitcnt lgkmcnt(0)
	v_mfma_f32_16x16x32_bf16 v[60:63], v[150:153], v[166:169], v[60:63]
	v_mfma_f32_16x16x32_bf16 v[56:59], v[158:161], v[166:169], v[56:59]
	v_mfma_f32_16x16x32_bf16 v[52:55], v[150:153], v[174:177], v[52:55]
	v_mfma_f32_16x16x32_bf16 v[48:51], v[158:161], v[174:177], v[48:51]
	v_mfma_f32_16x16x32_bf16 v[36:39], v[150:153], v[182:185], v[36:39]
	v_mfma_f32_16x16x32_bf16 v[32:35], v[158:161], v[182:185], v[32:35]
	v_mfma_f32_16x16x32_bf16 v[20:23], v[150:153], v[190:193], v[20:23]
	v_mfma_f32_16x16x32_bf16 v[16:19], v[158:161], v[190:193], v[16:19]
	v_mfma_f32_16x16x32_bf16 v[60:63], v[154:157], v[170:173], v[60:63]
	v_mfma_f32_16x16x32_bf16 v[56:59], v[162:165], v[170:173], v[56:59]
	v_mfma_f32_16x16x32_bf16 v[52:55], v[154:157], v[178:181], v[52:55]
	v_mfma_f32_16x16x32_bf16 v[48:51], v[162:165], v[178:181], v[48:51]
	v_mfma_f32_16x16x32_bf16 v[36:39], v[154:157], v[186:189], v[36:39]
	v_mfma_f32_16x16x32_bf16 v[32:35], v[162:165], v[186:189], v[32:35]
	v_mfma_f32_16x16x32_bf16 v[20:23], v[154:157], v[194:197], v[20:23]
	v_mfma_f32_16x16x32_bf16 v[16:19], v[162:165], v[194:197], v[16:19]
	s_setprio 0
	s_barrier
	s_add_u32 s30, s36, 0xa0000
	s_addc_u32 s31, s37, 0
	s_add_i32 s70, s55, s40
	v_lshl_add_u64 v[150:151], s[30:31], 0, v[130:131]
	s_mov_b32 m0, s70
	s_nop 0
	global_load_lds_dwordx4 v[150:151], off
	v_lshl_add_u64 v[150:151], s[30:31], 0, v[134:135]
	s_add_i32 m0, s70, 0x2000
	s_nop 0
	global_load_lds_dwordx4 v[150:151], off
	s_waitcnt vmcnt(10)
	s_barrier
	s_setprio 1
	v_mfma_f32_16x16x32_bf16 v[44:47], v[198:201], v[166:169], v[44:47]
	v_mfma_f32_16x16x32_bf16 v[40:43], v[210:213], v[166:169], v[40:43]
	v_mfma_f32_16x16x32_bf16 v[28:31], v[198:201], v[174:177], v[28:31]
	v_mfma_f32_16x16x32_bf16 v[24:27], v[210:213], v[174:177], v[24:27]
	v_mfma_f32_16x16x32_bf16 v[12:15], v[198:201], v[182:185], v[12:15]
	v_mfma_f32_16x16x32_bf16 v[8:11], v[210:213], v[182:185], v[8:11]
	v_mfma_f32_16x16x32_bf16 v[4:7], v[198:201], v[190:193], v[4:7]
	v_mfma_f32_16x16x32_bf16 v[0:3], v[210:213], v[190:193], v[0:3]
	v_mfma_f32_16x16x32_bf16 v[44:47], v[202:205], v[170:173], v[44:47]
	v_mfma_f32_16x16x32_bf16 v[40:43], v[214:217], v[170:173], v[40:43]
	v_mfma_f32_16x16x32_bf16 v[28:31], v[202:205], v[178:181], v[28:31]
	v_mfma_f32_16x16x32_bf16 v[24:27], v[214:217], v[178:181], v[24:27]
	v_mfma_f32_16x16x32_bf16 v[12:15], v[202:205], v[186:189], v[12:15]
	v_mfma_f32_16x16x32_bf16 v[8:11], v[214:217], v[186:189], v[8:11]
	v_mfma_f32_16x16x32_bf16 v[4:7], v[202:205], v[194:197], v[4:7]
	v_mfma_f32_16x16x32_bf16 v[0:3], v[214:217], v[194:197], v[0:3]
	s_setprio 0
	s_add_i32 s70, 0, 0x18000
	v_add_u32_e32 v162, s70, v146
	s_barrier
	ds_read_b128 v[150:153], v162
	ds_read_b128 v[154:157], v162 offset:1024
	ds_read_b128 v[158:161], v162 offset:2048
	ds_read_b128 v[162:165], v162 offset:3072
	s_add_u32 s30, s38, 0xa0000
	s_addc_u32 s31, s39, 0
	s_mov_b32 m0, s43
	v_lshl_add_u64 v[198:199], s[30:31], 0, v[128:129]
	ds_read_b128 v[166:169], v148 offset:32768
	ds_read_b128 v[170:173], v148 offset:33792
	ds_read_b128 v[174:177], v148 offset:34816
	ds_read_b128 v[178:181], v148 offset:35840
	ds_read_b128 v[182:185], v148 offset:36864
	ds_read_b128 v[186:189], v148 offset:37888
	ds_read_b128 v[190:193], v148 offset:38912
	ds_read_b128 v[194:197], v148 offset:39936
	global_load_lds_dwordx4 v[198:199], off
	v_lshl_add_u64 v[198:199], s[30:31], 0, v[132:133]
	s_mov_b32 m0, s44
	s_nop 0
	global_load_lds_dwordx4 v[198:199], off
	s_waitcnt lgkmcnt(8)
	s_waitcnt vmcnt(10)
	s_barrier
	s_waitcnt lgkmcnt(0)
	s_setprio 1
	s_waitcnt lgkmcnt(0)
	v_mfma_f32_16x16x32_bf16 v[124:127], v[150:153], v[166:169], v[124:127]
	v_mfma_f32_16x16x32_bf16 v[120:123], v[158:161], v[166:169], v[120:123]
	v_mfma_f32_16x16x32_bf16 v[116:119], v[150:153], v[174:177], v[116:119]
	v_mfma_f32_16x16x32_bf16 v[112:115], v[158:161], v[174:177], v[112:115]
	v_mfma_f32_16x16x32_bf16 v[100:103], v[150:153], v[182:185], v[100:103]
	v_mfma_f32_16x16x32_bf16 v[96:99], v[158:161], v[182:185], v[96:99]
	v_mfma_f32_16x16x32_bf16 v[84:87], v[150:153], v[190:193], v[84:87]
	v_mfma_f32_16x16x32_bf16 v[80:83], v[158:161], v[190:193], v[80:83]
	v_mfma_f32_16x16x32_bf16 v[124:127], v[154:157], v[170:173], v[124:127]
	v_mfma_f32_16x16x32_bf16 v[120:123], v[162:165], v[170:173], v[120:123]
	v_mfma_f32_16x16x32_bf16 v[116:119], v[154:157], v[178:181], v[116:119]
	v_mfma_f32_16x16x32_bf16 v[112:115], v[162:165], v[178:181], v[112:115]
	v_mfma_f32_16x16x32_bf16 v[100:103], v[154:157], v[186:189], v[100:103]
	v_mfma_f32_16x16x32_bf16 v[96:99], v[162:165], v[186:189], v[96:99]
	v_mfma_f32_16x16x32_bf16 v[84:87], v[154:157], v[194:197], v[84:87]
	v_mfma_f32_16x16x32_bf16 v[80:83], v[162:165], v[194:197], v[80:83]
	s_setprio 0
	s_barrier
	s_add_i32 s38, 0, 0x1c000
	s_add_i32 s30, s70, s40
	v_add_u32_e32 v214, s38, v146
	v_lshl_add_u64 v[206:207], v[206:207], 0, s[14:15]
	s_mov_b32 m0, s30
	ds_read_b128 v[198:201], v214
	ds_read_b128 v[202:205], v214 offset:1024
	ds_read_b128 v[210:213], v214 offset:2048
	ds_read_b128 v[214:217], v214 offset:3072
	global_load_lds_dwordx4 v[206:207], off
	v_lshl_add_u64 v[206:207], v[218:219], 0, s[14:15]
	s_add_i32 m0, s30, 0x2000
	s_nop 0
	global_load_lds_dwordx4 v[206:207], off
	s_waitcnt vmcnt(10)
	s_barrier
	s_waitcnt lgkmcnt(0)
	s_setprio 1
	s_waitcnt lgkmcnt(0)
	v_mfma_f32_16x16x32_bf16 v[108:111], v[198:201], v[166:169], v[108:111]
	v_mfma_f32_16x16x32_bf16 v[104:107], v[210:213], v[166:169], v[104:107]
	v_mfma_f32_16x16x32_bf16 v[92:95], v[198:201], v[174:177], v[92:95]
	v_mfma_f32_16x16x32_bf16 v[88:91], v[210:213], v[174:177], v[88:91]
	v_mfma_f32_16x16x32_bf16 v[76:79], v[198:201], v[182:185], v[76:79]
	v_mfma_f32_16x16x32_bf16 v[72:75], v[210:213], v[182:185], v[72:75]
	v_mfma_f32_16x16x32_bf16 v[68:71], v[198:201], v[190:193], v[68:71]
	v_mfma_f32_16x16x32_bf16 v[64:67], v[210:213], v[190:193], v[64:67]
	v_mfma_f32_16x16x32_bf16 v[108:111], v[202:205], v[170:173], v[108:111]
	v_mfma_f32_16x16x32_bf16 v[104:107], v[214:217], v[170:173], v[104:107]
	v_mfma_f32_16x16x32_bf16 v[92:95], v[202:205], v[178:181], v[92:95]
	v_mfma_f32_16x16x32_bf16 v[88:91], v[214:217], v[178:181], v[88:91]
	v_mfma_f32_16x16x32_bf16 v[76:79], v[202:205], v[186:189], v[76:79]
	v_mfma_f32_16x16x32_bf16 v[72:75], v[214:217], v[186:189], v[72:75]
	v_mfma_f32_16x16x32_bf16 v[68:71], v[202:205], v[194:197], v[68:71]
	v_mfma_f32_16x16x32_bf16 v[64:67], v[214:217], v[194:197], v[64:67]
	s_setprio 0
	s_mov_b32 m0, s52
	v_lshl_add_u64 v[206:207], v[220:221], 0, s[14:15]
	s_barrier
	ds_read_b128 v[166:169], v148 offset:49152
	ds_read_b128 v[170:173], v148 offset:50176
	ds_read_b128 v[174:177], v148 offset:51200
	ds_read_b128 v[178:181], v148 offset:52224
	ds_read_b128 v[182:185], v148 offset:53248
	ds_read_b128 v[186:189], v148 offset:54272
	ds_read_b128 v[190:193], v148 offset:55296
	ds_read_b128 v[194:197], v148 offset:56320
	global_load_lds_dwordx4 v[206:207], off
	v_lshl_add_u64 v[206:207], v[222:223], 0, s[14:15]
	s_mov_b32 m0, s53
	s_nop 0
	global_load_lds_dwordx4 v[206:207], off
	s_waitcnt vmcnt(10)
	s_barrier
	s_waitcnt lgkmcnt(0)
	s_setprio 1
	s_waitcnt lgkmcnt(0)
	v_mfma_f32_16x16x32_bf16 v[60:63], v[150:153], v[166:169], v[60:63]
	v_mfma_f32_16x16x32_bf16 v[56:59], v[158:161], v[166:169], v[56:59]
	v_mfma_f32_16x16x32_bf16 v[52:55], v[150:153], v[174:177], v[52:55]
	v_mfma_f32_16x16x32_bf16 v[48:51], v[158:161], v[174:177], v[48:51]
	v_mfma_f32_16x16x32_bf16 v[36:39], v[150:153], v[182:185], v[36:39]
	v_mfma_f32_16x16x32_bf16 v[32:35], v[158:161], v[182:185], v[32:35]
	v_mfma_f32_16x16x32_bf16 v[20:23], v[150:153], v[190:193], v[20:23]
	v_mfma_f32_16x16x32_bf16 v[16:19], v[158:161], v[190:193], v[16:19]
	v_mfma_f32_16x16x32_bf16 v[60:63], v[154:157], v[170:173], v[60:63]
	v_mfma_f32_16x16x32_bf16 v[56:59], v[162:165], v[170:173], v[56:59]
	v_mfma_f32_16x16x32_bf16 v[52:55], v[154:157], v[178:181], v[52:55]
	v_mfma_f32_16x16x32_bf16 v[48:51], v[162:165], v[178:181], v[48:51]
	v_mfma_f32_16x16x32_bf16 v[36:39], v[154:157], v[186:189], v[36:39]
	v_mfma_f32_16x16x32_bf16 v[32:35], v[162:165], v[186:189], v[32:35]
	v_mfma_f32_16x16x32_bf16 v[20:23], v[154:157], v[194:197], v[20:23]
	v_mfma_f32_16x16x32_bf16 v[16:19], v[162:165], v[194:197], v[16:19]
	s_setprio 0
	s_barrier
	s_add_u32 s30, s36, 0xa0080
	s_addc_u32 s31, s37, 0
	s_add_i32 s36, s38, s40
	v_lshl_add_u64 v[150:151], s[30:31], 0, v[130:131]
	s_mov_b32 m0, s36
	s_nop 0
	global_load_lds_dwordx4 v[150:151], off
	v_lshl_add_u64 v[150:151], s[30:31], 0, v[134:135]
	s_add_i32 m0, s36, 0x2000
	s_nop 0
	global_load_lds_dwordx4 v[150:151], off
	s_waitcnt vmcnt(10)
	s_barrier
	s_setprio 1
	v_mfma_f32_16x16x32_bf16 v[44:47], v[198:201], v[166:169], v[44:47]
	v_mfma_f32_16x16x32_bf16 v[40:43], v[210:213], v[166:169], v[40:43]
	v_mfma_f32_16x16x32_bf16 v[28:31], v[198:201], v[174:177], v[28:31]
	v_mfma_f32_16x16x32_bf16 v[24:27], v[210:213], v[174:177], v[24:27]
	v_mfma_f32_16x16x32_bf16 v[12:15], v[198:201], v[182:185], v[12:15]
	v_mfma_f32_16x16x32_bf16 v[8:11], v[210:213], v[182:185], v[8:11]
	v_mfma_f32_16x16x32_bf16 v[4:7], v[198:201], v[190:193], v[4:7]
	v_mfma_f32_16x16x32_bf16 v[0:3], v[210:213], v[190:193], v[0:3]
	v_mfma_f32_16x16x32_bf16 v[44:47], v[202:205], v[170:173], v[44:47]
	v_mfma_f32_16x16x32_bf16 v[40:43], v[214:217], v[170:173], v[40:43]
	v_mfma_f32_16x16x32_bf16 v[28:31], v[202:205], v[178:181], v[28:31]
	v_mfma_f32_16x16x32_bf16 v[24:27], v[214:217], v[178:181], v[24:27]
	v_mfma_f32_16x16x32_bf16 v[12:15], v[202:205], v[186:189], v[12:15]
	v_mfma_f32_16x16x32_bf16 v[8:11], v[214:217], v[186:189], v[8:11]
	v_mfma_f32_16x16x32_bf16 v[4:7], v[202:205], v[194:197], v[4:7]
	v_mfma_f32_16x16x32_bf16 v[0:3], v[214:217], v[194:197], v[0:3]
	s_setprio 0
	s_add_i32 s69, s69, 2
	s_add_u32 s67, s67, 0x100
	s_addc_u32 s68, s68, 0
	s_cmp_gt_u32 s69, 37
	s_mov_b64 s[30:31], s[34:35]
	s_barrier
	s_cbranch_scc0 .LBB0_1402
	v_mov_b32_e32 v150, v145
	v_mov_b32_e32 v151, v144
	s_lshl_b32 s30, s63, 8
	s_add_i32 s30, s30, s49
	v_add_u32_e32 v150, s30, v150
	s_lshl_b32 s30, s66, 8
	s_or_b32 s30, s30, s51
	v_lshl_add_u32 v152, v151, 3, s30
	v_ashrrev_i32_e32 v151, 31, v150
	v_lshlrev_b64 v[150:151], 12, v[150:151]
	v_ashrrev_i32_e32 v153, 31, v152
	v_lshl_add_u64 v[150:151], s[10:11], 0, v[150:151]
	v_lshl_add_u64 v[150:151], v[152:153], 1, v[150:151]
	v_cvt_pk_bf16_f32 v108, v108, v109
	v_cvt_pk_bf16_f32 v109, v110, v111
	v_cvt_pk_bf16_f32 v110, v104, v105
	v_cvt_pk_bf16_f32 v111, v106, v107
	global_store_dwordx4 v[150:151], v[108:111], off offset:256
	v_cvt_pk_bf16_f32 v92, v92, v93
	v_cvt_pk_bf16_f32 v93, v94, v95
	v_add_co_u32_e32 v110, vcc, s48, v150
	v_lshl_add_u64 v[108:109], v[150:151], 0, s[18:19]
	s_nop 0
	v_addc_co_u32_e32 v111, vcc, 0, v151, vcc
	v_cvt_pk_bf16_f32 v94, v88, v89
	v_cvt_pk_bf16_f32 v95, v90, v91
	global_store_dwordx4 v[108:109], v[92:95], off offset:256
	v_cvt_pk_bf16_f32 v76, v76, v77
	v_cvt_pk_bf16_f32 v77, v78, v79
	v_add_co_u32_e32 v94, vcc, s56, v150
	v_lshl_add_u64 v[92:93], v[150:151], 0, s[20:21]
	s_nop 0
	v_addc_co_u32_e32 v95, vcc, 0, v151, vcc
	v_cvt_pk_bf16_f32 v78, v72, v73
	v_cvt_pk_bf16_f32 v79, v74, v75
	global_store_dwordx4 v[92:93], v[76:79], off offset:256
	v_cvt_pk_bf16_f32 v60, v60, v61
	v_cvt_pk_bf16_f32 v61, v62, v63
	v_add_co_u32_e32 v78, vcc, s57, v150
	v_cvt_pk_bf16_f32 v62, v56, v57
	s_nop 0
	v_addc_co_u32_e32 v79, vcc, 0, v151, vcc
	v_add_co_u32_e32 v56, vcc, s59, v150
	v_cvt_pk_bf16_f32 v68, v68, v69
	v_cvt_pk_bf16_f32 v69, v70, v71
	v_cvt_pk_bf16_f32 v70, v64, v65
	v_lshl_add_u64 v[64:65], v[150:151], 0, s[24:25]
	v_addc_co_u32_e32 v57, vcc, 0, v151, vcc
	v_cvt_pk_bf16_f32 v44, v44, v45
	v_cvt_pk_bf16_f32 v45, v46, v47
	v_cvt_pk_bf16_f32 v46, v40, v41
	v_cvt_pk_bf16_f32 v47, v42, v43
	global_store_dwordx4 v[64:65], v[44:47], off offset:256
	v_cvt_pk_bf16_f32 v28, v28, v29
	v_cvt_pk_bf16_f32 v29, v30, v31
	v_add_co_u32_e32 v46, vcc, s60, v150
	v_lshl_add_u64 v[44:45], v[150:151], 0, s[26:27]
	s_nop 0
	v_addc_co_u32_e32 v47, vcc, 0, v151, vcc
	v_cvt_pk_bf16_f32 v30, v24, v25
	v_cvt_pk_bf16_f32 v31, v26, v27
	global_store_dwordx4 v[44:45], v[28:31], off offset:256
	v_cvt_pk_bf16_f32 v12, v12, v13
	v_cvt_pk_bf16_f32 v13, v14, v15
	v_add_co_u32_e32 v30, vcc, s61, v150
	v_lshl_add_u64 v[28:29], v[150:151], 0, s[8:9]
	s_nop 0
	v_addc_co_u32_e32 v31, vcc, 0, v151, vcc
	v_cvt_pk_bf16_f32 v14, v8, v9
	v_cvt_pk_bf16_f32 v15, v10, v11
	global_store_dwordx4 v[28:29], v[12:15], off offset:256
	v_cvt_pk_bf16_f32 v124, v124, v125
	v_cvt_pk_bf16_f32 v125, v126, v127
	v_add_co_u32_e32 v14, vcc, s62, v150
	v_cvt_pk_bf16_f32 v126, v120, v121
	s_nop 0
	v_addc_co_u32_e32 v15, vcc, 0, v151, vcc
	v_cvt_pk_bf16_f32 v127, v122, v123
	v_cvt_pk_bf16_f32 v104, v116, v117
	v_cvt_pk_bf16_f32 v105, v118, v119
	v_cvt_pk_bf16_f32 v106, v112, v113
	v_cvt_pk_bf16_f32 v107, v114, v115
	v_cvt_pk_bf16_f32 v88, v100, v101
	v_cvt_pk_bf16_f32 v89, v102, v103
	v_cvt_pk_bf16_f32 v90, v96, v97
	v_cvt_pk_bf16_f32 v91, v98, v99
	v_lshl_add_u64 v[76:77], v[150:151], 0, s[22:23]
	v_cvt_pk_bf16_f32 v72, v84, v85
	v_cvt_pk_bf16_f32 v73, v86, v87
	v_cvt_pk_bf16_f32 v74, v80, v81
	v_cvt_pk_bf16_f32 v75, v82, v83
	v_cvt_pk_bf16_f32 v71, v66, v67
	v_cvt_pk_bf16_f32 v63, v58, v59
	v_cvt_pk_bf16_f32 v40, v52, v53
	v_cvt_pk_bf16_f32 v41, v54, v55
	v_cvt_pk_bf16_f32 v42, v48, v49
	v_cvt_pk_bf16_f32 v43, v50, v51
	v_cvt_pk_bf16_f32 v24, v36, v37
	v_cvt_pk_bf16_f32 v25, v38, v39
	v_cvt_pk_bf16_f32 v26, v32, v33
	v_cvt_pk_bf16_f32 v27, v34, v35
	v_lshl_add_u64 v[12:13], v[150:151], 0, s[28:29]
	v_cvt_pk_bf16_f32 v8, v20, v21
	v_cvt_pk_bf16_f32 v9, v22, v23
	v_cvt_pk_bf16_f32 v10, v16, v17
	v_cvt_pk_bf16_f32 v11, v18, v19
	v_cvt_pk_bf16_f32 v4, v4, v5
	v_cvt_pk_bf16_f32 v5, v6, v7
	v_cvt_pk_bf16_f32 v6, v0, v1
	v_cvt_pk_bf16_f32 v7, v2, v3
	s_and_b64 vcc, exec, s[2:3]
	s_mov_b32 s66, s64
	s_mov_b32 s63, s65
	s_mov_b64 s[34:35], s[6:7]
	s_mov_b64 s[30:31], s[4:5]
	global_store_dwordx4 v[150:151], v[124:127], off
	global_store_dwordx4 v[110:111], v[104:107], off
	global_store_dwordx4 v[94:95], v[88:91], off
	global_store_dwordx4 v[78:79], v[72:75], off
	global_store_dwordx4 v[76:77], v[68:71], off offset:256
	global_store_dwordx4 v[56:57], v[60:63], off
	global_store_dwordx4 v[46:47], v[40:43], off
	global_store_dwordx4 v[30:31], v[24:27], off
	global_store_dwordx4 v[14:15], v[8:11], off
	global_store_dwordx4 v[12:13], v[4:7], off offset:256
	s_cbranch_vccz .LBB0_1391
	s_waitcnt vmcnt(0)
	s_cmpk_gt_u32 s33, 0xff
	s_cbranch_scc1 .LBB0_1406
	s_barrier
